# GLA output unit: epilogue loads issued before the last value-slice MFMAs and the row-norm reduction; that reduction (16 x 4 dependent LDS round trips) done as two batches of DPP butterflies plus one r
# speedup vs baseline: 1.0227x; 1.0090x over previous
.LBB0_4865:
	s_or_b64 exec, exec, s[26:27]
	v_or_b32_e32 v0, v73, v71
	v_mul_i32_i24_e32 v1, 0x190, v0
	v_lshlrev_b32_e32 v88, 4, v83
	v_mul_i32_i24_e32 v0, 0x90, v0
	v_add3_u32 v91, 0, v1, v88
	v_mul_lo_u32 v1, v54, s60
	v_add3_u32 v90, s62, v0, v88
	v_mul_lo_u32 v0, v54, s63
	v_add3_u32 v92, 0, v1, v88
	v_add3_u32 v89, s64, v0, v88
	v_mul_lo_u32 v0, v93, s60
	v_lshlrev_b32_e32 v1, 1, v64
	v_add3_u32 v96, 0, v0, v1
	v_mul_lo_u32 v0, v94, s60
	v_lshlrev_b32_e32 v1, 1, v66
	v_add3_u32 v97, 0, v0, v1
	v_mul_lo_u32 v0, v95, s60
	v_lshlrev_b32_e32 v1, 1, v68
	v_add3_u32 v98, 0, v0, v1
	v_mul_lo_u32 v0, v72, s63
	v_lshlrev_b32_e32 v1, 1, v99
	v_add3_u32 v72, s64, v0, v1
	v_mul_lo_u32 v0, v70, s63
	v_add3_u32 v70, s64, v0, v1
	v_add_u32_e32 v0, 0x80, v95
	v_mov_b64_e32 v[54:55], s[22:23]
	s_waitcnt lgkmcnt(0)
	s_barrier
	s_waitcnt vmcnt(7)
	ds_write_b128 v58, v[16:19]
	s_waitcnt vmcnt(6)
	ds_write_b128 v84, v[20:23]
	s_waitcnt vmcnt(5)
	ds_write_b128 v87, v[28:31]
	s_waitcnt vmcnt(4)
	ds_write_b128 v96, v[24:27]
	s_waitcnt vmcnt(3)
	ds_write_b128 v97, v[36:39]
	s_waitcnt vmcnt(2)
	ds_write_b128 v98, v[32:35]
	s_waitcnt vmcnt(1)
	ds_write_b16 v72, v44
	ds_write_b16_d16_hi v72, v44 offset:144
	ds_write_b16 v72, v45 offset:288
	ds_write_b16_d16_hi v72, v45 offset:432
	ds_write_b16 v72, v46 offset:576
	ds_write_b16_d16_hi v72, v46 offset:720
	ds_write_b16 v72, v47 offset:864
	ds_write_b16_d16_hi v72, v47 offset:1008
	s_waitcnt vmcnt(0)
	ds_write_b16 v70, v40
	ds_write_b16_d16_hi v70, v40 offset:144
	ds_write_b16 v70, v41 offset:288
	ds_write_b16_d16_hi v70, v41 offset:432
	ds_write_b16 v70, v42 offset:576
	ds_write_b16_d16_hi v70, v42 offset:720
	ds_write_b16 v70, v43 offset:864
	ds_write_b16_d16_hi v70, v43 offset:1008
	v_mad_i64_i32 v[0:1], s[2:3], v0, s54, v[54:55]
	v_lshlrev_b64 v[40:41], 1, v[68:69]
	v_lshl_add_u64 v[0:1], v[0:1], 0, v[40:41]
	s_waitcnt lgkmcnt(0)
	s_barrier
	global_load_dwordx4 v[16:19], v[0:1], off
	v_add_u32_e32 v0, 0x80, v94
	v_mad_i64_i32 v[0:1], s[2:3], v0, s54, v[54:55]
	v_lshlrev_b64 v[42:43], 1, v[66:67]
	v_lshl_add_u64 v[0:1], v[0:1], 0, v[42:43]
	global_load_dwordx4 v[20:23], v[0:1], off
	v_add_u32_e32 v0, 0x80, v93
	v_mad_i64_i32 v[0:1], s[2:3], v0, s54, v[54:55]
	v_lshlrev_b64 v[44:45], 1, v[64:65]
	v_lshl_add_u64 v[0:1], v[0:1], 0, v[44:45]
	global_load_dwordx4 v[24:27], v[0:1], off
	v_add_u32_e32 v0, 0x80, v81
	v_mad_i64_i32 v[0:1], s[2:3], v0, s54, v[54:55]
	v_lshlrev_b64 v[46:47], 1, v[52:53]
	v_lshl_add_u64 v[0:1], v[0:1], 0, v[46:47]
	global_load_dwordx4 v[28:31], v[0:1], off
	v_add_u32_e32 v0, 0x80, v80
	v_mad_i64_i32 v[0:1], s[2:3], v0, s54, v[54:55]
	v_lshlrev_b64 v[50:51], 1, v[50:51]
	v_lshl_add_u64 v[0:1], v[0:1], 0, v[50:51]
	global_load_dwordx4 v[32:35], v[0:1], off
	v_add_u32_e32 v0, 0x80, v79
	v_mad_i64_i32 v[0:1], s[2:3], v0, s54, v[54:55]
	v_lshlrev_b64 v[52:53], 1, v[48:49]
	v_lshl_add_u64 v[0:1], v[0:1], 0, v[52:53]
	global_load_dwordx4 v[36:39], v[0:1], off
	ds_read_b128 v[0:3], v91 offset:54272
	ds_read_b128 v[64:67], v91 offset:54304
	ds_read_b128 v[4:7], v92
	ds_read_b128 v[100:103], v92 offset:32
	s_waitcnt lgkmcnt(1)
	v_mfma_f32_32x32x16_bf16 v[0:15], v[0:3], v[4:7], 0
	s_waitcnt lgkmcnt(0)
	v_mfma_f32_32x32x16_bf16 v[0:15], v[64:67], v[100:103], v[0:15]
	ds_read_b128 v[64:67], v91 offset:54336
	ds_read_b128 v[100:103], v92 offset:64
	s_waitcnt lgkmcnt(0)
	v_mfma_f32_32x32x16_bf16 v[0:15], v[64:67], v[100:103], v[0:15]
	ds_read_b128 v[64:67], v91 offset:54368
	ds_read_b128 v[100:103], v92 offset:96
	s_waitcnt lgkmcnt(0)
	v_mfma_f32_32x32x16_bf16 v[0:15], v[64:67], v[100:103], v[0:15]
	ds_read_b128 v[64:67], v91 offset:54400
	ds_read_b128 v[100:103], v92 offset:128
	s_waitcnt lgkmcnt(0)
	v_mfma_f32_32x32x16_bf16 v[0:15], v[64:67], v[100:103], v[0:15]
	ds_read_b128 v[64:67], v91 offset:54432
	ds_read_b128 v[100:103], v92 offset:160
	s_waitcnt lgkmcnt(0)
	v_mfma_f32_32x32x16_bf16 v[0:15], v[64:67], v[100:103], v[0:15]
	ds_read_b128 v[64:67], v91 offset:54464
	ds_read_b128 v[100:103], v92 offset:192
	s_waitcnt lgkmcnt(0)
	v_mfma_f32_32x32x16_bf16 v[0:15], v[64:67], v[100:103], v[0:15]
	ds_read_b128 v[64:67], v91 offset:54496
	ds_read_b128 v[100:103], v92 offset:224
	s_waitcnt lgkmcnt(0)
	v_mfma_f32_32x32x16_bf16 v[0:15], v[64:67], v[100:103], v[0:15]
	ds_read_b128 v[64:67], v91 offset:54528
	ds_read_b128 v[100:103], v92 offset:256
	s_waitcnt lgkmcnt(0)
	v_mfma_f32_32x32x16_bf16 v[0:15], v[64:67], v[100:103], v[0:15]
	ds_read_b128 v[64:67], v91 offset:54560
	ds_read_b128 v[100:103], v92 offset:288
	s_waitcnt lgkmcnt(0)
	v_mfma_f32_32x32x16_bf16 v[0:15], v[64:67], v[100:103], v[0:15]
	ds_read_b128 v[64:67], v91 offset:54592
	ds_read_b128 v[100:103], v92 offset:320
	s_waitcnt lgkmcnt(0)
	v_mfma_f32_32x32x16_bf16 v[0:15], v[64:67], v[100:103], v[0:15]
	ds_read_b128 v[64:67], v91 offset:54624
	ds_read_b128 v[100:103], v92 offset:352
	s_waitcnt lgkmcnt(0)
	v_mfma_f32_32x32x16_bf16 v[0:15], v[64:67], v[100:103], v[0:15]
	ds_read_b128 v[64:67], v90
	ds_read_b128 v[100:103], v90 offset:32
	ds_read_b128 v[104:107], v89
	ds_read_b128 v[108:111], v89 offset:32
	s_waitcnt lgkmcnt(1)
	v_mfma_f32_32x32x16_bf16 v[0:15], v[64:67], v[104:107], v[0:15]
	s_waitcnt lgkmcnt(0)
	v_mfma_f32_32x32x16_bf16 v[0:15], v[100:103], v[108:111], v[0:15]
	ds_read_b128 v[64:67], v90 offset:64
	ds_read_b128 v[100:103], v89 offset:64
	s_waitcnt lgkmcnt(0)
	v_mfma_f32_32x32x16_bf16 v[0:15], v[64:67], v[100:103], v[0:15]
	ds_read_b128 v[64:67], v90 offset:96
	ds_read_b128 v[100:103], v89 offset:96
	s_waitcnt lgkmcnt(0)
	v_mfma_f32_32x32x16_bf16 v[0:15], v[64:67], v[100:103], v[0:15]
	global_load_dwordx4 v[64:67], v[62:63], off offset:3328
	global_load_dwordx4 v[100:103], v[60:61], off offset:3328
	s_barrier
	s_waitcnt vmcnt(2)
	ds_write_b128 v58, v[36:39]
	ds_write_b128 v84, v[32:35]
	ds_write_b128 v87, v[28:31]
	ds_write_b128 v96, v[24:27]
	ds_write_b128 v97, v[20:23]
	ds_write_b128 v98, v[16:19]
	s_waitcnt vmcnt(1)
	ds_write_b16 v72, v64
	ds_write_b16_d16_hi v72, v64 offset:144
	ds_write_b16 v72, v65 offset:288
	ds_write_b16_d16_hi v72, v65 offset:432
	ds_write_b16 v72, v66 offset:576
	ds_write_b16_d16_hi v72, v66 offset:720
	ds_write_b16 v72, v67 offset:864
	ds_write_b16_d16_hi v72, v67 offset:1008
	s_waitcnt vmcnt(0)
	ds_write_b16 v70, v100
	ds_write_b16_d16_hi v70, v100 offset:144
	ds_write_b16 v70, v101 offset:288
	ds_write_b16_d16_hi v70, v101 offset:432
	ds_write_b16 v70, v102 offset:576
	ds_write_b16_d16_hi v70, v102 offset:720
	ds_write_b16 v70, v103 offset:864
	ds_write_b16_d16_hi v70, v103 offset:1008
	v_add_u32_e32 v16, 0x100, v95
	v_mad_i64_i32 v[16:17], s[2:3], v16, s54, v[54:55]
	v_lshl_add_u64 v[16:17], v[16:17], 0, v[40:41]
	s_waitcnt lgkmcnt(0)
	s_barrier
	global_load_dwordx4 v[32:35], v[16:17], off
	v_add_u32_e32 v16, 0x100, v94
	v_mad_i64_i32 v[16:17], s[2:3], v16, s54, v[54:55]
	v_lshl_add_u64 v[16:17], v[16:17], 0, v[42:43]
	global_load_dwordx4 v[36:39], v[16:17], off
	v_add_u32_e32 v16, 0x100, v93
	v_mad_i64_i32 v[16:17], s[2:3], v16, s54, v[54:55]
	v_lshl_add_u64 v[16:17], v[16:17], 0, v[44:45]
	global_load_dwordx4 v[40:43], v[16:17], off
	v_add_u32_e32 v16, 0x100, v81
	v_mad_i64_i32 v[16:17], s[2:3], v16, s54, v[54:55]
	v_lshl_add_u64 v[16:17], v[16:17], 0, v[46:47]
	global_load_dwordx4 v[44:47], v[16:17], off
	v_add_u32_e32 v16, 0x100, v80
	v_mad_i64_i32 v[16:17], s[2:3], v16, s54, v[54:55]
	v_lshl_add_u64 v[16:17], v[16:17], 0, v[50:51]
	global_load_dwordx4 v[48:51], v[16:17], off
	v_add_u32_e32 v16, 0x100, v79
	v_mad_i64_i32 v[16:17], s[2:3], v16, s54, v[54:55]
	v_lshl_add_u64 v[16:17], v[16:17], 0, v[52:53]
	global_load_dwordx4 v[52:55], v[16:17], off
	ds_read_b128 v[16:19], v91 offset:54272
	ds_read_b128 v[64:67], v91 offset:54304
	ds_read_b128 v[20:23], v92
	ds_read_b128 v[100:103], v92 offset:32
	s_waitcnt lgkmcnt(1)
	v_mfma_f32_32x32x16_bf16 v[16:31], v[16:19], v[20:23], 0
	s_waitcnt lgkmcnt(0)
	v_mfma_f32_32x32x16_bf16 v[16:31], v[64:67], v[100:103], v[16:31]
	ds_read_b128 v[64:67], v91 offset:54336
	ds_read_b128 v[100:103], v92 offset:64
	s_waitcnt lgkmcnt(0)
	v_mfma_f32_32x32x16_bf16 v[16:31], v[64:67], v[100:103], v[16:31]
	ds_read_b128 v[64:67], v91 offset:54368
	ds_read_b128 v[100:103], v92 offset:96
	s_waitcnt lgkmcnt(0)
	v_mfma_f32_32x32x16_bf16 v[16:31], v[64:67], v[100:103], v[16:31]
	ds_read_b128 v[64:67], v91 offset:54400
	ds_read_b128 v[100:103], v92 offset:128
	s_waitcnt lgkmcnt(0)
	v_mfma_f32_32x32x16_bf16 v[16:31], v[64:67], v[100:103], v[16:31]
	ds_read_b128 v[64:67], v91 offset:54432
	ds_read_b128 v[100:103], v92 offset:160
	s_waitcnt lgkmcnt(0)
	v_mfma_f32_32x32x16_bf16 v[16:31], v[64:67], v[100:103], v[16:31]
	ds_read_b128 v[64:67], v91 offset:54464
	ds_read_b128 v[100:103], v92 offset:192
	s_waitcnt lgkmcnt(0)
	v_mfma_f32_32x32x16_bf16 v[16:31], v[64:67], v[100:103], v[16:31]
	ds_read_b128 v[64:67], v91 offset:54496
	ds_read_b128 v[100:103], v92 offset:224
	s_waitcnt lgkmcnt(0)
	v_mfma_f32_32x32x16_bf16 v[16:31], v[64:67], v[100:103], v[16:31]
	ds_read_b128 v[64:67], v91 offset:54528
	ds_read_b128 v[100:103], v92 offset:256
	s_waitcnt lgkmcnt(0)
	v_mfma_f32_32x32x16_bf16 v[16:31], v[64:67], v[100:103], v[16:31]
	ds_read_b128 v[64:67], v91 offset:54560
	ds_read_b128 v[100:103], v92 offset:288
	s_waitcnt lgkmcnt(0)
	v_mfma_f32_32x32x16_bf16 v[16:31], v[64:67], v[100:103], v[16:31]
	ds_read_b128 v[64:67], v91 offset:54592
	ds_read_b128 v[100:103], v92 offset:320
	s_waitcnt lgkmcnt(0)
	v_mfma_f32_32x32x16_bf16 v[16:31], v[64:67], v[100:103], v[16:31]
	ds_read_b128 v[64:67], v91 offset:54624
	ds_read_b128 v[100:103], v92 offset:352
	s_waitcnt lgkmcnt(0)
	v_mfma_f32_32x32x16_bf16 v[16:31], v[64:67], v[100:103], v[16:31]
	ds_read_b128 v[64:67], v90
	ds_read_b128 v[100:103], v90 offset:32
	ds_read_b128 v[104:107], v89
	ds_read_b128 v[108:111], v89 offset:32
	s_waitcnt lgkmcnt(1)
	v_mfma_f32_32x32x16_bf16 v[16:31], v[64:67], v[104:107], v[16:31]
	s_waitcnt lgkmcnt(0)
	v_mfma_f32_32x32x16_bf16 v[16:31], v[100:103], v[108:111], v[16:31]
	ds_read_b128 v[64:67], v90 offset:64
	ds_read_b128 v[100:103], v89 offset:64
	s_waitcnt lgkmcnt(0)
	v_mfma_f32_32x32x16_bf16 v[16:31], v[64:67], v[100:103], v[16:31]
	ds_read_b128 v[64:67], v90 offset:96
	ds_read_b128 v[100:103], v89 offset:96
	s_waitcnt lgkmcnt(0)
	v_mfma_f32_32x32x16_bf16 v[16:31], v[64:67], v[100:103], v[16:31]
	global_load_dwordx4 v[62:65], v[62:63], off offset:3584
	s_nop 0
	global_load_dwordx4 v[66:69], v[60:61], off offset:3584
	s_barrier
	s_waitcnt vmcnt(2)
	ds_write_b128 v58, v[52:55]
	ds_write_b128 v84, v[48:51]
	ds_write_b128 v87, v[44:47]
	ds_write_b128 v96, v[40:43]
	ds_write_b128 v97, v[36:39]
	ds_write_b128 v98, v[32:35]
	s_waitcnt vmcnt(1)
	ds_write_b16 v72, v62
	ds_write_b16_d16_hi v72, v62 offset:144
	ds_write_b16 v72, v63 offset:288
	ds_write_b16_d16_hi v72, v63 offset:432
	ds_write_b16 v72, v64 offset:576
	ds_write_b16_d16_hi v72, v64 offset:720
	ds_write_b16 v72, v65 offset:864
	ds_write_b16_d16_hi v72, v65 offset:1008
	s_waitcnt vmcnt(0)
	v_lshl_or_b32 v144, v83, 2, v73
	v_or_b32_e32 v145, s0, v71
	v_add_u32_e32 v145, v82, v145
	v_or_b32_e32 v144, s66, v144
	v_mul_lo_u32 v201, v144, s49
	v_lshlrev_b32_e32 v202, 12, v144
	v_lshl_add_u32 v201, v145, 1, v201
	v_lshl_add_u32 v202, v145, 1, v202
	v_lshlrev_b32_e32 v144, 2, v145
	global_load_dword v195, v144, s[34:35]
	global_load_dword v196, v144, s[34:35] offset:512
	global_load_dword v197, v144, s[34:35] offset:1024
	global_load_dword v198, v144, s[20:21]
	global_load_dword v199, v144, s[20:21] offset:512
	global_load_dword v200, v144, s[20:21] offset:1024
	v_add_u32_e32 v201, 0x1000, v201
	global_load_ushort v205, v201, s[36:37] offset:2048
	global_load_ushort v206, v201, s[36:37] offset:2304
	global_load_ushort v207, v201, s[36:37] offset:2560
	v_add_u32_e32 v201, 0x2a00, v201
	global_load_ushort v208, v201, s[36:37] offset:2048
	global_load_ushort v209, v201, s[36:37] offset:2304
	global_load_ushort v210, v201, s[36:37] offset:2560
	v_add_u32_e32 v201, 0x2a00, v201
	global_load_ushort v211, v201, s[36:37] offset:2048
	global_load_ushort v212, v201, s[36:37] offset:2304
	global_load_ushort v213, v201, s[36:37] offset:2560
	v_add_u32_e32 v201, 0x2a00, v201
	global_load_ushort v214, v201, s[36:37] offset:2048
	global_load_ushort v215, v201, s[36:37] offset:2304
	global_load_ushort v216, v201, s[36:37] offset:2560
	v_add_u32_e32 v201, 0xd200, v201
	global_load_ushort v217, v201, s[36:37] offset:2048
	global_load_ushort v218, v201, s[36:37] offset:2304
	global_load_ushort v219, v201, s[36:37] offset:2560
	v_add_u32_e32 v201, 0x2a00, v201
	global_load_ushort v220, v201, s[36:37] offset:2048
	global_load_ushort v221, v201, s[36:37] offset:2304
	global_load_ushort v222, v201, s[36:37] offset:2560
	v_add_u32_e32 v201, 0x2a00, v201
	global_load_ushort v223, v201, s[36:37] offset:2048
	global_load_ushort v224, v201, s[36:37] offset:2304
	global_load_ushort v225, v201, s[36:37] offset:2560
	v_add_u32_e32 v201, 0x2a00, v201
	global_load_ushort v226, v201, s[36:37] offset:2048
	global_load_ushort v227, v201, s[36:37] offset:2304
	global_load_ushort v228, v201, s[36:37] offset:2560
	v_add_u32_e32 v201, 0xd200, v201
	global_load_ushort v229, v201, s[36:37] offset:2048
	global_load_ushort v230, v201, s[36:37] offset:2304
	global_load_ushort v231, v201, s[36:37] offset:2560
	v_add_u32_e32 v201, 0x2a00, v201
	global_load_ushort v232, v201, s[36:37] offset:2048
	global_load_ushort v233, v201, s[36:37] offset:2304
	global_load_ushort v234, v201, s[36:37] offset:2560
	v_add_u32_e32 v201, 0x2a00, v201
	global_load_ushort v235, v201, s[36:37] offset:2048
	global_load_ushort v236, v201, s[36:37] offset:2304
	global_load_ushort v237, v201, s[36:37] offset:2560
	v_add_u32_e32 v201, 0x2a00, v201
	global_load_ushort v238, v201, s[36:37] offset:2048
	global_load_ushort v239, v201, s[36:37] offset:2304
	global_load_ushort v240, v201, s[36:37] offset:2560
	v_add_u32_e32 v201, 0xd200, v201
	global_load_ushort v241, v201, s[36:37] offset:2048
	global_load_ushort v242, v201, s[36:37] offset:2304
	global_load_ushort v243, v201, s[36:37] offset:2560
	v_add_u32_e32 v201, 0x2a00, v201
	global_load_ushort v244, v201, s[36:37] offset:2048
	global_load_ushort v245, v201, s[36:37] offset:2304
	global_load_ushort v246, v201, s[36:37] offset:2560
	v_add_u32_e32 v201, 0x2a00, v201
	global_load_ushort v247, v201, s[36:37] offset:2048
	global_load_ushort v248, v201, s[36:37] offset:2304
	global_load_ushort v249, v201, s[36:37] offset:2560
	v_add_u32_e32 v201, 0x2a00, v201
	global_load_ushort v250, v201, s[36:37] offset:2048
	global_load_ushort v251, v201, s[36:37] offset:2304
	global_load_ushort v194, v201, s[36:37] offset:2560
	ds_write_b16 v70, v66
	ds_write_b16_d16_hi v70, v66 offset:144
	ds_write_b16 v70, v67 offset:288
	ds_write_b16_d16_hi v70, v67 offset:432
	ds_write_b16 v70, v68 offset:576
	ds_write_b16_d16_hi v70, v68 offset:720
	ds_write_b16 v70, v69 offset:864
	ds_write_b16_d16_hi v70, v69 offset:1008
	s_waitcnt lgkmcnt(0)
	s_barrier
	ds_read_b128 v[32:35], v91 offset:54272
	ds_read_b128 v[48:51], v91 offset:54304
	ds_read_b128 v[36:39], v92
	ds_read_b128 v[52:55], v92 offset:32
	s_waitcnt lgkmcnt(1)
	v_mfma_f32_32x32x16_bf16 v[32:47], v[32:35], v[36:39], 0
	s_waitcnt lgkmcnt(0)
	v_mfma_f32_32x32x16_bf16 v[32:47], v[48:51], v[52:55], v[32:47]
	ds_read_b128 v[48:51], v91 offset:54336
	ds_read_b128 v[52:55], v92 offset:64
	s_waitcnt lgkmcnt(0)
	v_mfma_f32_32x32x16_bf16 v[32:47], v[48:51], v[52:55], v[32:47]
	ds_read_b128 v[48:51], v91 offset:54368
	ds_read_b128 v[52:55], v92 offset:96
	s_waitcnt lgkmcnt(0)
	v_mfma_f32_32x32x16_bf16 v[32:47], v[48:51], v[52:55], v[32:47]
	ds_read_b128 v[48:51], v91 offset:54400
	ds_read_b128 v[52:55], v92 offset:128
	s_waitcnt lgkmcnt(0)
	v_mfma_f32_32x32x16_bf16 v[32:47], v[48:51], v[52:55], v[32:47]
	ds_read_b128 v[48:51], v91 offset:54432
	ds_read_b128 v[52:55], v92 offset:160
	s_waitcnt lgkmcnt(0)
	v_mfma_f32_32x32x16_bf16 v[32:47], v[48:51], v[52:55], v[32:47]
	ds_read_b128 v[48:51], v91 offset:54464
	ds_read_b128 v[52:55], v92 offset:192
	s_waitcnt lgkmcnt(0)
	v_mfma_f32_32x32x16_bf16 v[32:47], v[48:51], v[52:55], v[32:47]
	ds_read_b128 v[48:51], v91 offset:54496
	ds_read_b128 v[52:55], v92 offset:224
	s_waitcnt lgkmcnt(0)
	v_mfma_f32_32x32x16_bf16 v[32:47], v[48:51], v[52:55], v[32:47]
	ds_read_b128 v[48:51], v91 offset:54528
	ds_read_b128 v[52:55], v92 offset:256
	s_waitcnt lgkmcnt(0)
	v_mfma_f32_32x32x16_bf16 v[32:47], v[48:51], v[52:55], v[32:47]
	ds_read_b128 v[48:51], v91 offset:54560
	ds_read_b128 v[52:55], v92 offset:288
	s_waitcnt lgkmcnt(0)
	v_mfma_f32_32x32x16_bf16 v[32:47], v[48:51], v[52:55], v[32:47]
	ds_read_b128 v[48:51], v91 offset:54592
	ds_read_b128 v[52:55], v92 offset:320
	s_waitcnt lgkmcnt(0)
	v_mfma_f32_32x32x16_bf16 v[32:47], v[48:51], v[52:55], v[32:47]
	ds_read_b128 v[48:51], v91 offset:54624
	ds_read_b128 v[52:55], v92 offset:352
	s_waitcnt lgkmcnt(0)
	v_mfma_f32_32x32x16_bf16 v[32:47], v[48:51], v[52:55], v[32:47]
	ds_read_b128 v[48:51], v90
	ds_read_b128 v[52:55], v90 offset:32
	ds_read_b128 v[60:63], v89
	ds_read_b128 v[64:67], v89 offset:32
	s_waitcnt lgkmcnt(1)
	v_mfma_f32_32x32x16_bf16 v[32:47], v[48:51], v[60:63], v[32:47]
	s_waitcnt lgkmcnt(0)
	v_mfma_f32_32x32x16_bf16 v[32:47], v[52:55], v[64:67], v[32:47]
	ds_read_b128 v[48:51], v90 offset:64
	ds_read_b128 v[52:55], v89 offset:64
	s_waitcnt lgkmcnt(0)
	v_mfma_f32_32x32x16_bf16 v[32:47], v[48:51], v[52:55], v[32:47]
	ds_read_b128 v[48:51], v90 offset:96
	ds_read_b128 v[52:55], v89 offset:96
	s_waitcnt lgkmcnt(0)
	s_barrier
	v_mfma_f32_32x32x16_bf16 v[32:47], v[48:51], v[52:55], v[32:47]
	v_xor_b32_e32 v69, 16, v204
	v_lshlrev_b32_e32 v49, 7, v85
	v_lshlrev_b32_e32 v69, 2, v69
	v_add3_u32 v49, v88, v86, v49
	v_lshl_add_u32 v70, v49, 2, 0
	v_add_u32_e32 v70, 0x20800, v70
	v_mul_f32_e32 v48, v16, v16
	v_mul_f32_e32 v49, v17, v17
	v_mul_f32_e32 v50, v18, v18
	v_mul_f32_e32 v51, v19, v19
	v_mul_f32_e32 v52, v20, v20
	v_mul_f32_e32 v53, v21, v21
	v_mul_f32_e32 v54, v22, v22
	v_mul_f32_e32 v55, v23, v23
	v_fmac_f32_e32 v48, v0, v0
	v_fmac_f32_e32 v49, v1, v1
	v_fmac_f32_e32 v50, v2, v2
	v_fmac_f32_e32 v51, v3, v3
	v_fmac_f32_e32 v52, v4, v4
	v_fmac_f32_e32 v53, v5, v5
	v_fmac_f32_e32 v54, v6, v6
	v_fmac_f32_e32 v55, v7, v7
	v_fmac_f32_e32 v48, v32, v32
	v_fmac_f32_e32 v49, v33, v33
	v_fmac_f32_e32 v50, v34, v34
	v_fmac_f32_e32 v51, v35, v35
	v_fmac_f32_e32 v52, v36, v36
	v_fmac_f32_e32 v53, v37, v37
	v_fmac_f32_e32 v54, v38, v38
	v_fmac_f32_e32 v55, v39, v39
	v_add_f32_dpp v48, v48, v48 quad_perm:[1,0,3,2] row_mask:0xf bank_mask:0xf
	v_add_f32_dpp v49, v49, v49 quad_perm:[1,0,3,2] row_mask:0xf bank_mask:0xf
	v_add_f32_dpp v50, v50, v50 quad_perm:[1,0,3,2] row_mask:0xf bank_mask:0xf
	v_add_f32_dpp v51, v51, v51 quad_perm:[1,0,3,2] row_mask:0xf bank_mask:0xf
	v_add_f32_dpp v52, v52, v52 quad_perm:[1,0,3,2] row_mask:0xf bank_mask:0xf
	v_add_f32_dpp v53, v53, v53 quad_perm:[1,0,3,2] row_mask:0xf bank_mask:0xf
	v_add_f32_dpp v54, v54, v54 quad_perm:[1,0,3,2] row_mask:0xf bank_mask:0xf
	v_add_f32_dpp v55, v55, v55 quad_perm:[1,0,3,2] row_mask:0xf bank_mask:0xf
	v_add_f32_dpp v48, v48, v48 quad_perm:[2,3,0,1] row_mask:0xf bank_mask:0xf
	v_add_f32_dpp v49, v49, v49 quad_perm:[2,3,0,1] row_mask:0xf bank_mask:0xf
	v_add_f32_dpp v50, v50, v50 quad_perm:[2,3,0,1] row_mask:0xf bank_mask:0xf
	v_add_f32_dpp v51, v51, v51 quad_perm:[2,3,0,1] row_mask:0xf bank_mask:0xf
	v_add_f32_dpp v52, v52, v52 quad_perm:[2,3,0,1] row_mask:0xf bank_mask:0xf
	v_add_f32_dpp v53, v53, v53 quad_perm:[2,3,0,1] row_mask:0xf bank_mask:0xf
	v_add_f32_dpp v54, v54, v54 quad_perm:[2,3,0,1] row_mask:0xf bank_mask:0xf
	v_add_f32_dpp v55, v55, v55 quad_perm:[2,3,0,1] row_mask:0xf bank_mask:0xf
	v_add_f32_dpp v48, v48, v48 row_ror:4 row_mask:0xf bank_mask:0xf
	v_add_f32_dpp v49, v49, v49 row_ror:4 row_mask:0xf bank_mask:0xf
	v_add_f32_dpp v50, v50, v50 row_ror:4 row_mask:0xf bank_mask:0xf
	v_add_f32_dpp v51, v51, v51 row_ror:4 row_mask:0xf bank_mask:0xf
	v_add_f32_dpp v52, v52, v52 row_ror:4 row_mask:0xf bank_mask:0xf
	v_add_f32_dpp v53, v53, v53 row_ror:4 row_mask:0xf bank_mask:0xf
	v_add_f32_dpp v54, v54, v54 row_ror:4 row_mask:0xf bank_mask:0xf
	v_add_f32_dpp v55, v55, v55 row_ror:4 row_mask:0xf bank_mask:0xf
	v_add_f32_dpp v48, v48, v48 row_ror:8 row_mask:0xf bank_mask:0xf
	v_add_f32_dpp v49, v49, v49 row_ror:8 row_mask:0xf bank_mask:0xf
	v_add_f32_dpp v50, v50, v50 row_ror:8 row_mask:0xf bank_mask:0xf
	v_add_f32_dpp v51, v51, v51 row_ror:8 row_mask:0xf bank_mask:0xf
	v_add_f32_dpp v52, v52, v52 row_ror:8 row_mask:0xf bank_mask:0xf
	v_add_f32_dpp v53, v53, v53 row_ror:8 row_mask:0xf bank_mask:0xf
	v_add_f32_dpp v54, v54, v54 row_ror:8 row_mask:0xf bank_mask:0xf
	v_add_f32_dpp v55, v55, v55 row_ror:8 row_mask:0xf bank_mask:0xf
	ds_bpermute_b32 v60, v69, v48
	ds_bpermute_b32 v61, v69, v49
	ds_bpermute_b32 v62, v69, v50
	ds_bpermute_b32 v63, v69, v51
	ds_bpermute_b32 v64, v69, v52
	ds_bpermute_b32 v65, v69, v53
	ds_bpermute_b32 v66, v69, v54
	ds_bpermute_b32 v67, v69, v55
	s_waitcnt lgkmcnt(0)
	v_cmp_eq_u32_e32 vcc, 0, v71
	s_and_saveexec_b64 s[22:23], vcc
	v_add_f32_e32 v60, v48, v60
	ds_write_b32 v70, v60
	v_add_f32_e32 v61, v49, v61
	ds_write_b32 v70, v61 offset:16
	v_add_f32_e32 v62, v50, v62
	ds_write_b32 v70, v62 offset:32
	v_add_f32_e32 v63, v51, v63
	ds_write_b32 v70, v63 offset:48
	v_add_f32_e32 v64, v52, v64
	ds_write_b32 v70, v64 offset:128
	v_add_f32_e32 v65, v53, v65
	ds_write_b32 v70, v65 offset:144
	v_add_f32_e32 v66, v54, v66
	ds_write_b32 v70, v66 offset:160
	v_add_f32_e32 v67, v55, v67
	ds_write_b32 v70, v67 offset:176
	s_or_b64 exec, exec, s[22:23]
	v_mul_f32_e32 v48, v24, v24
	v_mul_f32_e32 v49, v25, v25
	v_mul_f32_e32 v50, v26, v26
	v_mul_f32_e32 v51, v27, v27
	v_mul_f32_e32 v52, v28, v28
	v_mul_f32_e32 v53, v29, v29
	v_mul_f32_e32 v54, v30, v30
	v_mul_f32_e32 v55, v31, v31
	v_fmac_f32_e32 v48, v8, v8
	v_fmac_f32_e32 v49, v9, v9
	v_fmac_f32_e32 v50, v10, v10
	v_fmac_f32_e32 v51, v11, v11
	v_fmac_f32_e32 v52, v12, v12
	v_fmac_f32_e32 v53, v13, v13
	v_fmac_f32_e32 v54, v14, v14
	v_fmac_f32_e32 v55, v15, v15
	v_fmac_f32_e32 v48, v40, v40
	v_fmac_f32_e32 v49, v41, v41
	v_fmac_f32_e32 v50, v42, v42
	v_fmac_f32_e32 v51, v43, v43
	v_fmac_f32_e32 v52, v44, v44
	v_fmac_f32_e32 v53, v45, v45
	v_fmac_f32_e32 v54, v46, v46
	v_fmac_f32_e32 v55, v47, v47
	v_add_f32_dpp v48, v48, v48 quad_perm:[1,0,3,2] row_mask:0xf bank_mask:0xf
	v_add_f32_dpp v49, v49, v49 quad_perm:[1,0,3,2] row_mask:0xf bank_mask:0xf
	v_add_f32_dpp v50, v50, v50 quad_perm:[1,0,3,2] row_mask:0xf bank_mask:0xf
	v_add_f32_dpp v51, v51, v51 quad_perm:[1,0,3,2] row_mask:0xf bank_mask:0xf
	v_add_f32_dpp v52, v52, v52 quad_perm:[1,0,3,2] row_mask:0xf bank_mask:0xf
	v_add_f32_dpp v53, v53, v53 quad_perm:[1,0,3,2] row_mask:0xf bank_mask:0xf
	v_add_f32_dpp v54, v54, v54 quad_perm:[1,0,3,2] row_mask:0xf bank_mask:0xf
	v_add_f32_dpp v55, v55, v55 quad_perm:[1,0,3,2] row_mask:0xf bank_mask:0xf
	v_add_f32_dpp v48, v48, v48 quad_perm:[2,3,0,1] row_mask:0xf bank_mask:0xf
	v_add_f32_dpp v49, v49, v49 quad_perm:[2,3,0,1] row_mask:0xf bank_mask:0xf
	v_add_f32_dpp v50, v50, v50 quad_perm:[2,3,0,1] row_mask:0xf bank_mask:0xf
	v_add_f32_dpp v51, v51, v51 quad_perm:[2,3,0,1] row_mask:0xf bank_mask:0xf
	v_add_f32_dpp v52, v52, v52 quad_perm:[2,3,0,1] row_mask:0xf bank_mask:0xf
	v_add_f32_dpp v53, v53, v53 quad_perm:[2,3,0,1] row_mask:0xf bank_mask:0xf
	v_add_f32_dpp v54, v54, v54 quad_perm:[2,3,0,1] row_mask:0xf bank_mask:0xf
	v_add_f32_dpp v55, v55, v55 quad_perm:[2,3,0,1] row_mask:0xf bank_mask:0xf
	v_add_f32_dpp v48, v48, v48 row_ror:4 row_mask:0xf bank_mask:0xf
	v_add_f32_dpp v49, v49, v49 row_ror:4 row_mask:0xf bank_mask:0xf
	v_add_f32_dpp v50, v50, v50 row_ror:4 row_mask:0xf bank_mask:0xf
	v_add_f32_dpp v51, v51, v51 row_ror:4 row_mask:0xf bank_mask:0xf
	v_add_f32_dpp v52, v52, v52 row_ror:4 row_mask:0xf bank_mask:0xf
	v_add_f32_dpp v53, v53, v53 row_ror:4 row_mask:0xf bank_mask:0xf
	v_add_f32_dpp v54, v54, v54 row_ror:4 row_mask:0xf bank_mask:0xf
	v_add_f32_dpp v55, v55, v55 row_ror:4 row_mask:0xf bank_mask:0xf
	v_add_f32_dpp v48, v48, v48 row_ror:8 row_mask:0xf bank_mask:0xf
	v_add_f32_dpp v49, v49, v49 row_ror:8 row_mask:0xf bank_mask:0xf
	v_add_f32_dpp v50, v50, v50 row_ror:8 row_mask:0xf bank_mask:0xf
	v_add_f32_dpp v51, v51, v51 row_ror:8 row_mask:0xf bank_mask:0xf
	v_add_f32_dpp v52, v52, v52 row_ror:8 row_mask:0xf bank_mask:0xf
	v_add_f32_dpp v53, v53, v53 row_ror:8 row_mask:0xf bank_mask:0xf
	v_add_f32_dpp v54, v54, v54 row_ror:8 row_mask:0xf bank_mask:0xf
	v_add_f32_dpp v55, v55, v55 row_ror:8 row_mask:0xf bank_mask:0xf
	ds_bpermute_b32 v60, v69, v48
	ds_bpermute_b32 v61, v69, v49
	ds_bpermute_b32 v62, v69, v50
	ds_bpermute_b32 v63, v69, v51
	ds_bpermute_b32 v64, v69, v52
	ds_bpermute_b32 v65, v69, v53
	ds_bpermute_b32 v66, v69, v54
	ds_bpermute_b32 v67, v69, v55
	s_waitcnt lgkmcnt(0)
	v_cmp_eq_u32_e32 vcc, 0, v71
	s_and_saveexec_b64 s[22:23], vcc
	v_add_f32_e32 v60, v48, v60
	ds_write_b32 v70, v60 offset:256
	v_add_f32_e32 v61, v49, v61
	ds_write_b32 v70, v61 offset:272
	v_add_f32_e32 v62, v50, v62
	ds_write_b32 v70, v62 offset:288
	v_add_f32_e32 v63, v51, v63
	ds_write_b32 v70, v63 offset:304
	v_add_f32_e32 v64, v52, v64
	ds_write_b32 v70, v64 offset:384
	v_add_f32_e32 v65, v53, v65
	ds_write_b32 v70, v65 offset:400
	v_add_f32_e32 v66, v54, v66
	ds_write_b32 v70, v66 offset:416
	v_add_f32_e32 v67, v55, v67
	ds_write_b32 v70, v67 offset:432
	s_or_b64 exec, exec, s[22:23]
	v_lshl_or_b32 v62, v83, 2, v73
	v_or_b32_e32 v48, s0, v71
	v_add_u32_e32 v52, v82, v48
	v_or_b32_e32 v54, s66, v62
	v_mov_b64_e32 v[48:49], s[36:37]
	v_mad_i64_i32 v[48:49], s[0:1], v54, s49, v[48:49]
	v_ashrrev_i32_e32 v53, 31, v52
	v_lshl_add_u64 v[60:61], v[52:53], 1, v[48:49]
	v_add_co_u32_e32 v48, vcc, s50, v60
	s_waitcnt lgkmcnt(0)
	s_nop 0
	v_addc_co_u32_e32 v49, vcc, 0, v61, vcc
	s_barrier
	s_mov_b32 s98, 0x55555555
	s_mov_b32 s99, 0x55555555
	v_lshl_add_u32 v203, v62, 4, 0
	v_add_u32_e32 v203, 0x20800, v203
	ds_read_b128 v[64:67], v203
	s_waitcnt lgkmcnt(0)
	v_add_f32_e32 v68, v64, v65
	v_add_f32_e32 v69, v66, v67
	ds_read_b128 v[64:67], v203 offset:16
	v_add_f32_e32 v68, v68, v69
	v_fmamk_f32 v68, v68, 0x3b2aaaab, v76
	v_mul_f32_e32 v69, 0x4b800000, v68
	v_cmp_gt_f32_e32 vcc, s56, v68
	s_nop 1
	v_cndmask_b32_e32 v68, v68, v69, vcc
	v_rsq_f32_e32 v68, v68
	s_nop 0
	v_mul_f32_e32 v69, 0x45800000, v68
	v_cndmask_b32_e32 v63, v68, v69, vcc
	s_waitcnt vmcnt(47)
	v_lshlrev_b32_e32 v205, 16, v205
	v_add_f32_e32 v205, v195, v205
	v_mul_f32_e32 v68, 0xbfb8aa3b, v205
	v_exp_f32_e32 v68, v68
	v_mul_f32_e32 v0, v0, v63
	v_add_f32_e32 v68, 1.0, v68
	v_div_scale_f32 v69, s[0:1], v68, v68, v205
	v_div_scale_f32 v71, vcc, v205, v68, v205
	v_rcp_f32_e32 v70, v69
	v_mul_f32_e32 v0, v198, v0
	v_fma_f32 v50, -v69, v70, 1.0
	v_fmac_f32_e32 v70, v50, v70
	v_mul_f32_e32 v50, v71, v70
	v_fma_f32 v51, -v69, v50, v71
	v_fmac_f32_e32 v50, v51, v70
	v_fma_f32 v69, -v69, v50, v71
	v_div_fmas_f32 v69, v69, v70, v50
	v_div_fixup_f32 v205, v69, v68, v205
	v_mul_f32_e32 v0, v205, v0
	s_waitcnt vmcnt(46)
	v_lshlrev_b32_e32 v206, 16, v206
	v_add_f32_e32 v206, v196, v206
	v_mul_f32_e32 v68, 0xbfb8aa3b, v206
	v_exp_f32_e32 v68, v68
	v_mul_f32_e32 v16, v16, v63
	v_add_f32_e32 v68, 1.0, v68
	v_div_scale_f32 v69, s[0:1], v68, v68, v206
	v_div_scale_f32 v71, vcc, v206, v68, v206
	v_rcp_f32_e32 v70, v69
	v_mul_f32_e32 v16, v199, v16
	v_fma_f32 v50, -v69, v70, 1.0
	v_fmac_f32_e32 v70, v50, v70
	v_mul_f32_e32 v50, v71, v70
	v_fma_f32 v51, -v69, v50, v71
	v_fmac_f32_e32 v50, v51, v70
	v_fma_f32 v69, -v69, v50, v71
	v_div_fmas_f32 v69, v69, v70, v50
	v_div_fixup_f32 v206, v69, v68, v206
	v_mul_f32_e32 v16, v206, v16
	s_waitcnt vmcnt(45)
	v_lshlrev_b32_e32 v207, 16, v207
	v_add_f32_e32 v207, v197, v207
	v_mul_f32_e32 v68, 0xbfb8aa3b, v207
	v_exp_f32_e32 v68, v68
	v_mul_f32_e32 v32, v32, v63
	v_add_f32_e32 v68, 1.0, v68
	v_div_scale_f32 v69, s[0:1], v68, v68, v207
	v_div_scale_f32 v71, vcc, v207, v68, v207
	v_rcp_f32_e32 v70, v69
	v_mul_f32_e32 v32, v200, v32
	v_fma_f32 v50, -v69, v70, 1.0
	v_fmac_f32_e32 v70, v50, v70
	v_mul_f32_e32 v50, v71, v70
	v_fma_f32 v51, -v69, v50, v71
	v_fmac_f32_e32 v50, v51, v70
	v_fma_f32 v69, -v69, v50, v71
	v_div_fmas_f32 v69, v69, v70, v50
	v_div_fixup_f32 v207, v69, v68, v207
	v_mul_f32_e32 v32, v207, v32
	s_nop 1
	v_mov_b32_dpp v68, v0 quad_perm:[1,0,3,2] row_mask:0xf bank_mask:0xf
	v_mov_b32_dpp v69, v16 quad_perm:[1,0,3,2] row_mask:0xf bank_mask:0xf
	v_mov_b32_dpp v70, v32 quad_perm:[1,0,3,2] row_mask:0xf bank_mask:0xf
	s_nop 0
	v_cvt_pk_bf16_f32 v0, v0, v68
	v_cvt_pk_bf16_f32 v16, v16, v69
	v_cvt_pk_bf16_f32 v32, v32, v70
	s_mov_b64 exec, s[98:99]
	global_store_dword v202, v0, s[38:39]
	global_store_dword v202, v16, s[38:39] offset:256
	global_store_dword v202, v32, s[38:39] offset:512
	s_mov_b64 exec, -1
	v_add_u32_e32 v202, 0x1000, v202
	s_waitcnt lgkmcnt(0)
	v_add_f32_e32 v68, v64, v65
	v_add_f32_e32 v69, v66, v67
	ds_read_b128 v[64:67], v203 offset:32
	v_add_f32_e32 v68, v68, v69
	v_fmamk_f32 v68, v68, 0x3b2aaaab, v76
	v_mul_f32_e32 v69, 0x4b800000, v68
	v_cmp_gt_f32_e32 vcc, s56, v68
	s_nop 1
	v_cndmask_b32_e32 v68, v68, v69, vcc
	v_rsq_f32_e32 v68, v68
	s_nop 0
	v_mul_f32_e32 v69, 0x45800000, v68
	v_cndmask_b32_e32 v63, v68, v69, vcc
	s_waitcnt vmcnt(47)
	v_lshlrev_b32_e32 v208, 16, v208
	v_add_f32_e32 v208, v195, v208
	v_mul_f32_e32 v68, 0xbfb8aa3b, v208
	v_exp_f32_e32 v68, v68
	v_mul_f32_e32 v1, v1, v63
	v_add_f32_e32 v68, 1.0, v68
	v_div_scale_f32 v69, s[0:1], v68, v68, v208
	v_div_scale_f32 v71, vcc, v208, v68, v208
	v_rcp_f32_e32 v70, v69
	v_mul_f32_e32 v1, v198, v1
	v_fma_f32 v50, -v69, v70, 1.0
	v_fmac_f32_e32 v70, v50, v70
	v_mul_f32_e32 v50, v71, v70
	v_fma_f32 v51, -v69, v50, v71
	v_fmac_f32_e32 v50, v51, v70
	v_fma_f32 v69, -v69, v50, v71
	v_div_fmas_f32 v69, v69, v70, v50
	v_div_fixup_f32 v208, v69, v68, v208
	v_mul_f32_e32 v1, v208, v1
	s_waitcnt vmcnt(46)
	v_lshlrev_b32_e32 v209, 16, v209
	v_add_f32_e32 v209, v196, v209
	v_mul_f32_e32 v68, 0xbfb8aa3b, v209
	v_exp_f32_e32 v68, v68
	v_mul_f32_e32 v17, v17, v63
	v_add_f32_e32 v68, 1.0, v68
	v_div_scale_f32 v69, s[0:1], v68, v68, v209
	v_div_scale_f32 v71, vcc, v209, v68, v209
	v_rcp_f32_e32 v70, v69
	v_mul_f32_e32 v17, v199, v17
	v_fma_f32 v50, -v69, v70, 1.0
	v_fmac_f32_e32 v70, v50, v70
	v_mul_f32_e32 v50, v71, v70
	v_fma_f32 v51, -v69, v50, v71
	v_fmac_f32_e32 v50, v51, v70
	v_fma_f32 v69, -v69, v50, v71
	v_div_fmas_f32 v69, v69, v70, v50
	v_div_fixup_f32 v209, v69, v68, v209
	v_mul_f32_e32 v17, v209, v17
	s_waitcnt vmcnt(45)
	v_lshlrev_b32_e32 v210, 16, v210
	v_add_f32_e32 v210, v197, v210
	v_mul_f32_e32 v68, 0xbfb8aa3b, v210
	v_exp_f32_e32 v68, v68
	v_mul_f32_e32 v33, v33, v63
	v_add_f32_e32 v68, 1.0, v68
	v_div_scale_f32 v69, s[0:1], v68, v68, v210
	v_div_scale_f32 v71, vcc, v210, v68, v210
	v_rcp_f32_e32 v70, v69
	v_mul_f32_e32 v33, v200, v33
	v_fma_f32 v50, -v69, v70, 1.0
	v_fmac_f32_e32 v70, v50, v70
	v_mul_f32_e32 v50, v71, v70
	v_fma_f32 v51, -v69, v50, v71
	v_fmac_f32_e32 v50, v51, v70
	v_fma_f32 v69, -v69, v50, v71
	v_div_fmas_f32 v69, v69, v70, v50
	v_div_fixup_f32 v210, v69, v68, v210
	v_mul_f32_e32 v33, v210, v33
	s_nop 1
	v_mov_b32_dpp v68, v1 quad_perm:[1,0,3,2] row_mask:0xf bank_mask:0xf
	v_mov_b32_dpp v69, v17 quad_perm:[1,0,3,2] row_mask:0xf bank_mask:0xf
	v_mov_b32_dpp v70, v33 quad_perm:[1,0,3,2] row_mask:0xf bank_mask:0xf
	s_nop 0
	v_cvt_pk_bf16_f32 v1, v1, v68
	v_cvt_pk_bf16_f32 v17, v17, v69
	v_cvt_pk_bf16_f32 v33, v33, v70
	s_mov_b64 exec, s[98:99]
	global_store_dword v202, v1, s[38:39]
	global_store_dword v202, v17, s[38:39] offset:256
	global_store_dword v202, v33, s[38:39] offset:512
	s_mov_b64 exec, -1
	v_add_u32_e32 v202, 0x1000, v202
	s_waitcnt lgkmcnt(0)
	v_add_f32_e32 v68, v64, v65
	v_add_f32_e32 v69, v66, v67
	ds_read_b128 v[64:67], v203 offset:48
	v_add_f32_e32 v68, v68, v69
	v_fmamk_f32 v68, v68, 0x3b2aaaab, v76
	v_mul_f32_e32 v69, 0x4b800000, v68
	v_cmp_gt_f32_e32 vcc, s56, v68
	s_nop 1
	v_cndmask_b32_e32 v68, v68, v69, vcc
	v_rsq_f32_e32 v68, v68
	s_nop 0
	v_mul_f32_e32 v69, 0x45800000, v68
	v_cndmask_b32_e32 v63, v68, v69, vcc
	s_waitcnt vmcnt(47)
	v_lshlrev_b32_e32 v211, 16, v211
	v_add_f32_e32 v211, v195, v211
	v_mul_f32_e32 v68, 0xbfb8aa3b, v211
	v_exp_f32_e32 v68, v68
	v_mul_f32_e32 v2, v2, v63
	v_add_f32_e32 v68, 1.0, v68
	v_div_scale_f32 v69, s[0:1], v68, v68, v211
	v_div_scale_f32 v71, vcc, v211, v68, v211
	v_rcp_f32_e32 v70, v69
	v_mul_f32_e32 v2, v198, v2
	v_fma_f32 v50, -v69, v70, 1.0
	v_fmac_f32_e32 v70, v50, v70
	v_mul_f32_e32 v50, v71, v70
	v_fma_f32 v51, -v69, v50, v71
	v_fmac_f32_e32 v50, v51, v70
	v_fma_f32 v69, -v69, v50, v71
	v_div_fmas_f32 v69, v69, v70, v50
	v_div_fixup_f32 v211, v69, v68, v211
	v_mul_f32_e32 v2, v211, v2
	s_waitcnt vmcnt(46)
	v_lshlrev_b32_e32 v212, 16, v212
	v_add_f32_e32 v212, v196, v212
	v_mul_f32_e32 v68, 0xbfb8aa3b, v212
	v_exp_f32_e32 v68, v68
	v_mul_f32_e32 v18, v18, v63
	v_add_f32_e32 v68, 1.0, v68
	v_div_scale_f32 v69, s[0:1], v68, v68, v212
	v_div_scale_f32 v71, vcc, v212, v68, v212
	v_rcp_f32_e32 v70, v69
	v_mul_f32_e32 v18, v199, v18
	v_fma_f32 v50, -v69, v70, 1.0
	v_fmac_f32_e32 v70, v50, v70
	v_mul_f32_e32 v50, v71, v70
	v_fma_f32 v51, -v69, v50, v71
	v_fmac_f32_e32 v50, v51, v70
	v_fma_f32 v69, -v69, v50, v71
	v_div_fmas_f32 v69, v69, v70, v50
	v_div_fixup_f32 v212, v69, v68, v212
	v_mul_f32_e32 v18, v212, v18
	s_waitcnt vmcnt(45)
	v_lshlrev_b32_e32 v213, 16, v213
	v_add_f32_e32 v213, v197, v213
	v_mul_f32_e32 v68, 0xbfb8aa3b, v213
	v_exp_f32_e32 v68, v68
	v_mul_f32_e32 v34, v34, v63
	v_add_f32_e32 v68, 1.0, v68
	v_div_scale_f32 v69, s[0:1], v68, v68, v213
	v_div_scale_f32 v71, vcc, v213, v68, v213
	v_rcp_f32_e32 v70, v69
	v_mul_f32_e32 v34, v200, v34
	v_fma_f32 v50, -v69, v70, 1.0
	v_fmac_f32_e32 v70, v50, v70
	v_mul_f32_e32 v50, v71, v70
	v_fma_f32 v51, -v69, v50, v71
	v_fmac_f32_e32 v50, v51, v70
	v_fma_f32 v69, -v69, v50, v71
	v_div_fmas_f32 v69, v69, v70, v50
	v_div_fixup_f32 v213, v69, v68, v213
	v_mul_f32_e32 v34, v213, v34
	s_nop 1
	v_mov_b32_dpp v68, v2 quad_perm:[1,0,3,2] row_mask:0xf bank_mask:0xf
	v_mov_b32_dpp v69, v18 quad_perm:[1,0,3,2] row_mask:0xf bank_mask:0xf
	v_mov_b32_dpp v70, v34 quad_perm:[1,0,3,2] row_mask:0xf bank_mask:0xf
	s_nop 0
	v_cvt_pk_bf16_f32 v2, v2, v68
	v_cvt_pk_bf16_f32 v18, v18, v69
	v_cvt_pk_bf16_f32 v34, v34, v70
	s_mov_b64 exec, s[98:99]
	global_store_dword v202, v2, s[38:39]
	global_store_dword v202, v18, s[38:39] offset:256
	global_store_dword v202, v34, s[38:39] offset:512
	s_mov_b64 exec, -1
	v_add_u32_e32 v202, 0x1000, v202
	s_waitcnt lgkmcnt(0)
	v_add_f32_e32 v68, v64, v65
	v_add_f32_e32 v69, v66, v67
	ds_read_b128 v[64:67], v203 offset:128
	v_add_f32_e32 v68, v68, v69
	v_fmamk_f32 v68, v68, 0x3b2aaaab, v76
	v_mul_f32_e32 v69, 0x4b800000, v68
	v_cmp_gt_f32_e32 vcc, s56, v68
	s_nop 1
	v_cndmask_b32_e32 v68, v68, v69, vcc
	v_rsq_f32_e32 v68, v68
	s_nop 0
	v_mul_f32_e32 v69, 0x45800000, v68
	v_cndmask_b32_e32 v63, v68, v69, vcc
	s_waitcnt vmcnt(47)
	v_lshlrev_b32_e32 v214, 16, v214
	v_add_f32_e32 v214, v195, v214
	v_mul_f32_e32 v68, 0xbfb8aa3b, v214
	v_exp_f32_e32 v68, v68
	v_mul_f32_e32 v3, v3, v63
	v_add_f32_e32 v68, 1.0, v68
	v_div_scale_f32 v69, s[0:1], v68, v68, v214
	v_div_scale_f32 v71, vcc, v214, v68, v214
	v_rcp_f32_e32 v70, v69
	v_mul_f32_e32 v3, v198, v3
	v_fma_f32 v50, -v69, v70, 1.0
	v_fmac_f32_e32 v70, v50, v70
	v_mul_f32_e32 v50, v71, v70
	v_fma_f32 v51, -v69, v50, v71
	v_fmac_f32_e32 v50, v51, v70
	v_fma_f32 v69, -v69, v50, v71
	v_div_fmas_f32 v69, v69, v70, v50
	v_div_fixup_f32 v214, v69, v68, v214
	v_mul_f32_e32 v3, v214, v3
	s_waitcnt vmcnt(46)
	v_lshlrev_b32_e32 v215, 16, v215
	v_add_f32_e32 v215, v196, v215
	v_mul_f32_e32 v68, 0xbfb8aa3b, v215
	v_exp_f32_e32 v68, v68
	v_mul_f32_e32 v19, v19, v63
	v_add_f32_e32 v68, 1.0, v68
	v_div_scale_f32 v69, s[0:1], v68, v68, v215
	v_div_scale_f32 v71, vcc, v215, v68, v215
	v_rcp_f32_e32 v70, v69
	v_mul_f32_e32 v19, v199, v19
	v_fma_f32 v50, -v69, v70, 1.0
	v_fmac_f32_e32 v70, v50, v70
	v_mul_f32_e32 v50, v71, v70
	v_fma_f32 v51, -v69, v50, v71
	v_fmac_f32_e32 v50, v51, v70
	v_fma_f32 v69, -v69, v50, v71
	v_div_fmas_f32 v69, v69, v70, v50
	v_div_fixup_f32 v215, v69, v68, v215
	v_mul_f32_e32 v19, v215, v19
	s_waitcnt vmcnt(45)
	v_lshlrev_b32_e32 v216, 16, v216
	v_add_f32_e32 v216, v197, v216
	v_mul_f32_e32 v68, 0xbfb8aa3b, v216
	v_exp_f32_e32 v68, v68
	v_mul_f32_e32 v35, v35, v63
	v_add_f32_e32 v68, 1.0, v68
	v_div_scale_f32 v69, s[0:1], v68, v68, v216
	v_div_scale_f32 v71, vcc, v216, v68, v216
	v_rcp_f32_e32 v70, v69
	v_mul_f32_e32 v35, v200, v35
	v_fma_f32 v50, -v69, v70, 1.0
	v_fmac_f32_e32 v70, v50, v70
	v_mul_f32_e32 v50, v71, v70
	v_fma_f32 v51, -v69, v50, v71
	v_fmac_f32_e32 v50, v51, v70
	v_fma_f32 v69, -v69, v50, v71
	v_div_fmas_f32 v69, v69, v70, v50
	v_div_fixup_f32 v216, v69, v68, v216
	v_mul_f32_e32 v35, v216, v35
	s_nop 1
	v_mov_b32_dpp v68, v3 quad_perm:[1,0,3,2] row_mask:0xf bank_mask:0xf
	v_mov_b32_dpp v69, v19 quad_perm:[1,0,3,2] row_mask:0xf bank_mask:0xf
	v_mov_b32_dpp v70, v35 quad_perm:[1,0,3,2] row_mask:0xf bank_mask:0xf
	s_nop 0
	v_cvt_pk_bf16_f32 v3, v3, v68
	v_cvt_pk_bf16_f32 v19, v19, v69
	v_cvt_pk_bf16_f32 v35, v35, v70
	s_mov_b64 exec, s[98:99]
	global_store_dword v202, v3, s[38:39]
	global_store_dword v202, v19, s[38:39] offset:256
	global_store_dword v202, v35, s[38:39] offset:512
	s_mov_b64 exec, -1
	v_add_u32_e32 v202, 0x5000, v202
	s_waitcnt lgkmcnt(0)
	v_add_f32_e32 v68, v64, v65
	v_add_f32_e32 v69, v66, v67
	ds_read_b128 v[64:67], v203 offset:144
	v_add_f32_e32 v68, v68, v69
	v_fmamk_f32 v68, v68, 0x3b2aaaab, v76
	v_mul_f32_e32 v69, 0x4b800000, v68
	v_cmp_gt_f32_e32 vcc, s56, v68
	s_nop 1
	v_cndmask_b32_e32 v68, v68, v69, vcc
	v_rsq_f32_e32 v68, v68
	s_nop 0
	v_mul_f32_e32 v69, 0x45800000, v68
	v_cndmask_b32_e32 v63, v68, v69, vcc
	s_waitcnt vmcnt(47)
	v_lshlrev_b32_e32 v217, 16, v217
	v_add_f32_e32 v217, v195, v217
	v_mul_f32_e32 v68, 0xbfb8aa3b, v217
	v_exp_f32_e32 v68, v68
	v_mul_f32_e32 v4, v4, v63
	v_add_f32_e32 v68, 1.0, v68
	v_div_scale_f32 v69, s[0:1], v68, v68, v217
	v_div_scale_f32 v71, vcc, v217, v68, v217
	v_rcp_f32_e32 v70, v69
	v_mul_f32_e32 v4, v198, v4
	v_fma_f32 v50, -v69, v70, 1.0
	v_fmac_f32_e32 v70, v50, v70
	v_mul_f32_e32 v50, v71, v70
	v_fma_f32 v51, -v69, v50, v71
	v_fmac_f32_e32 v50, v51, v70
	v_fma_f32 v69, -v69, v50, v71
	v_div_fmas_f32 v69, v69, v70, v50
	v_div_fixup_f32 v217, v69, v68, v217
	v_mul_f32_e32 v4, v217, v4
	s_waitcnt vmcnt(46)
	v_lshlrev_b32_e32 v218, 16, v218
	v_add_f32_e32 v218, v196, v218
	v_mul_f32_e32 v68, 0xbfb8aa3b, v218
	v_exp_f32_e32 v68, v68
	v_mul_f32_e32 v20, v20, v63
	v_add_f32_e32 v68, 1.0, v68
	v_div_scale_f32 v69, s[0:1], v68, v68, v218
	v_div_scale_f32 v71, vcc, v218, v68, v218
	v_rcp_f32_e32 v70, v69
	v_mul_f32_e32 v20, v199, v20
	v_fma_f32 v50, -v69, v70, 1.0
	v_fmac_f32_e32 v70, v50, v70
	v_mul_f32_e32 v50, v71, v70
	v_fma_f32 v51, -v69, v50, v71
	v_fmac_f32_e32 v50, v51, v70
	v_fma_f32 v69, -v69, v50, v71
	v_div_fmas_f32 v69, v69, v70, v50
	v_div_fixup_f32 v218, v69, v68, v218
	v_mul_f32_e32 v20, v218, v20
	s_waitcnt vmcnt(45)
	v_lshlrev_b32_e32 v219, 16, v219
	v_add_f32_e32 v219, v197, v219
	v_mul_f32_e32 v68, 0xbfb8aa3b, v219
	v_exp_f32_e32 v68, v68
	v_mul_f32_e32 v36, v36, v63
	v_add_f32_e32 v68, 1.0, v68
	v_div_scale_f32 v69, s[0:1], v68, v68, v219
	v_div_scale_f32 v71, vcc, v219, v68, v219
	v_rcp_f32_e32 v70, v69
	v_mul_f32_e32 v36, v200, v36
	v_fma_f32 v50, -v69, v70, 1.0
	v_fmac_f32_e32 v70, v50, v70
	v_mul_f32_e32 v50, v71, v70
	v_fma_f32 v51, -v69, v50, v71
	v_fmac_f32_e32 v50, v51, v70
	v_fma_f32 v69, -v69, v50, v71
	v_div_fmas_f32 v69, v69, v70, v50
	v_div_fixup_f32 v219, v69, v68, v219
	v_mul_f32_e32 v36, v219, v36
	s_nop 1
	v_mov_b32_dpp v68, v4 quad_perm:[1,0,3,2] row_mask:0xf bank_mask:0xf
	v_mov_b32_dpp v69, v20 quad_perm:[1,0,3,2] row_mask:0xf bank_mask:0xf
	v_mov_b32_dpp v70, v36 quad_perm:[1,0,3,2] row_mask:0xf bank_mask:0xf
	s_nop 0
	v_cvt_pk_bf16_f32 v4, v4, v68
	v_cvt_pk_bf16_f32 v20, v20, v69
	v_cvt_pk_bf16_f32 v36, v36, v70
	s_mov_b64 exec, s[98:99]
	global_store_dword v202, v4, s[38:39]
	global_store_dword v202, v20, s[38:39] offset:256
	global_store_dword v202, v36, s[38:39] offset:512
	s_mov_b64 exec, -1
	v_add_u32_e32 v202, 0x1000, v202
	s_waitcnt lgkmcnt(0)
	v_add_f32_e32 v68, v64, v65
	v_add_f32_e32 v69, v66, v67
	ds_read_b128 v[64:67], v203 offset:160
	v_add_f32_e32 v68, v68, v69
	v_fmamk_f32 v68, v68, 0x3b2aaaab, v76
	v_mul_f32_e32 v69, 0x4b800000, v68
	v_cmp_gt_f32_e32 vcc, s56, v68
	s_nop 1
	v_cndmask_b32_e32 v68, v68, v69, vcc
	v_rsq_f32_e32 v68, v68
	s_nop 0
	v_mul_f32_e32 v69, 0x45800000, v68
	v_cndmask_b32_e32 v63, v68, v69, vcc
	s_waitcnt vmcnt(47)
	v_lshlrev_b32_e32 v220, 16, v220
	v_add_f32_e32 v220, v195, v220
	v_mul_f32_e32 v68, 0xbfb8aa3b, v220
	v_exp_f32_e32 v68, v68
	v_mul_f32_e32 v5, v5, v63
	v_add_f32_e32 v68, 1.0, v68
	v_div_scale_f32 v69, s[0:1], v68, v68, v220
	v_div_scale_f32 v71, vcc, v220, v68, v220
	v_rcp_f32_e32 v70, v69
	v_mul_f32_e32 v5, v198, v5
	v_fma_f32 v50, -v69, v70, 1.0
	v_fmac_f32_e32 v70, v50, v70
	v_mul_f32_e32 v50, v71, v70
	v_fma_f32 v51, -v69, v50, v71
	v_fmac_f32_e32 v50, v51, v70
	v_fma_f32 v69, -v69, v50, v71
	v_div_fmas_f32 v69, v69, v70, v50
	v_div_fixup_f32 v220, v69, v68, v220
	v_mul_f32_e32 v5, v220, v5
	s_waitcnt vmcnt(46)
	v_lshlrev_b32_e32 v221, 16, v221
	v_add_f32_e32 v221, v196, v221
	v_mul_f32_e32 v68, 0xbfb8aa3b, v221
	v_exp_f32_e32 v68, v68
	v_mul_f32_e32 v21, v21, v63
	v_add_f32_e32 v68, 1.0, v68
	v_div_scale_f32 v69, s[0:1], v68, v68, v221
	v_div_scale_f32 v71, vcc, v221, v68, v221
	v_rcp_f32_e32 v70, v69
	v_mul_f32_e32 v21, v199, v21
	v_fma_f32 v50, -v69, v70, 1.0
	v_fmac_f32_e32 v70, v50, v70
	v_mul_f32_e32 v50, v71, v70
	v_fma_f32 v51, -v69, v50, v71
	v_fmac_f32_e32 v50, v51, v70
	v_fma_f32 v69, -v69, v50, v71
	v_div_fmas_f32 v69, v69, v70, v50
	v_div_fixup_f32 v221, v69, v68, v221
	v_mul_f32_e32 v21, v221, v21
	s_waitcnt vmcnt(45)
	v_lshlrev_b32_e32 v222, 16, v222
	v_add_f32_e32 v222, v197, v222
	v_mul_f32_e32 v68, 0xbfb8aa3b, v222
	v_exp_f32_e32 v68, v68
	v_mul_f32_e32 v37, v37, v63
	v_add_f32_e32 v68, 1.0, v68
	v_div_scale_f32 v69, s[0:1], v68, v68, v222
	v_div_scale_f32 v71, vcc, v222, v68, v222
	v_rcp_f32_e32 v70, v69
	v_mul_f32_e32 v37, v200, v37
	v_fma_f32 v50, -v69, v70, 1.0
	v_fmac_f32_e32 v70, v50, v70
	v_mul_f32_e32 v50, v71, v70
	v_fma_f32 v51, -v69, v50, v71
	v_fmac_f32_e32 v50, v51, v70
	v_fma_f32 v69, -v69, v50, v71
	v_div_fmas_f32 v69, v69, v70, v50
	v_div_fixup_f32 v222, v69, v68, v222
	v_mul_f32_e32 v37, v222, v37
	s_nop 1
	v_mov_b32_dpp v68, v5 quad_perm:[1,0,3,2] row_mask:0xf bank_mask:0xf
	v_mov_b32_dpp v69, v21 quad_perm:[1,0,3,2] row_mask:0xf bank_mask:0xf
	v_mov_b32_dpp v70, v37 quad_perm:[1,0,3,2] row_mask:0xf bank_mask:0xf
	s_nop 0
	v_cvt_pk_bf16_f32 v5, v5, v68
	v_cvt_pk_bf16_f32 v21, v21, v69
	v_cvt_pk_bf16_f32 v37, v37, v70
	s_mov_b64 exec, s[98:99]
	global_store_dword v202, v5, s[38:39]
	global_store_dword v202, v21, s[38:39] offset:256
	global_store_dword v202, v37, s[38:39] offset:512
	s_mov_b64 exec, -1
	v_add_u32_e32 v202, 0x1000, v202
	s_waitcnt lgkmcnt(0)
	v_add_f32_e32 v68, v64, v65
	v_add_f32_e32 v69, v66, v67
	ds_read_b128 v[64:67], v203 offset:176
	v_add_f32_e32 v68, v68, v69
	v_fmamk_f32 v68, v68, 0x3b2aaaab, v76
	v_mul_f32_e32 v69, 0x4b800000, v68
	v_cmp_gt_f32_e32 vcc, s56, v68
	s_nop 1
	v_cndmask_b32_e32 v68, v68, v69, vcc
	v_rsq_f32_e32 v68, v68
	s_nop 0
	v_mul_f32_e32 v69, 0x45800000, v68
	v_cndmask_b32_e32 v63, v68, v69, vcc
	s_waitcnt vmcnt(47)
	v_lshlrev_b32_e32 v223, 16, v223
	v_add_f32_e32 v223, v195, v223
	v_mul_f32_e32 v68, 0xbfb8aa3b, v223
	v_exp_f32_e32 v68, v68
	v_mul_f32_e32 v6, v6, v63
	v_add_f32_e32 v68, 1.0, v68
	v_div_scale_f32 v69, s[0:1], v68, v68, v223
	v_div_scale_f32 v71, vcc, v223, v68, v223
	v_rcp_f32_e32 v70, v69
	v_mul_f32_e32 v6, v198, v6
	v_fma_f32 v50, -v69, v70, 1.0
	v_fmac_f32_e32 v70, v50, v70
	v_mul_f32_e32 v50, v71, v70
	v_fma_f32 v51, -v69, v50, v71
	v_fmac_f32_e32 v50, v51, v70
	v_fma_f32 v69, -v69, v50, v71
	v_div_fmas_f32 v69, v69, v70, v50
	v_div_fixup_f32 v223, v69, v68, v223
	v_mul_f32_e32 v6, v223, v6
	s_waitcnt vmcnt(46)
	v_lshlrev_b32_e32 v224, 16, v224
	v_add_f32_e32 v224, v196, v224
	v_mul_f32_e32 v68, 0xbfb8aa3b, v224
	v_exp_f32_e32 v68, v68
	v_mul_f32_e32 v22, v22, v63
	v_add_f32_e32 v68, 1.0, v68
	v_div_scale_f32 v69, s[0:1], v68, v68, v224
	v_div_scale_f32 v71, vcc, v224, v68, v224
	v_rcp_f32_e32 v70, v69
	v_mul_f32_e32 v22, v199, v22
	v_fma_f32 v50, -v69, v70, 1.0
	v_fmac_f32_e32 v70, v50, v70
	v_mul_f32_e32 v50, v71, v70
	v_fma_f32 v51, -v69, v50, v71
	v_fmac_f32_e32 v50, v51, v70
	v_fma_f32 v69, -v69, v50, v71
	v_div_fmas_f32 v69, v69, v70, v50
	v_div_fixup_f32 v224, v69, v68, v224
	v_mul_f32_e32 v22, v224, v22
	s_waitcnt vmcnt(45)
	v_lshlrev_b32_e32 v225, 16, v225
	v_add_f32_e32 v225, v197, v225
	v_mul_f32_e32 v68, 0xbfb8aa3b, v225
	v_exp_f32_e32 v68, v68
	v_mul_f32_e32 v38, v38, v63
	v_add_f32_e32 v68, 1.0, v68
	v_div_scale_f32 v69, s[0:1], v68, v68, v225
	v_div_scale_f32 v71, vcc, v225, v68, v225
	v_rcp_f32_e32 v70, v69
	v_mul_f32_e32 v38, v200, v38
	v_fma_f32 v50, -v69, v70, 1.0
	v_fmac_f32_e32 v70, v50, v70
	v_mul_f32_e32 v50, v71, v70
	v_fma_f32 v51, -v69, v50, v71
	v_fmac_f32_e32 v50, v51, v70
	v_fma_f32 v69, -v69, v50, v71
	v_div_fmas_f32 v69, v69, v70, v50
	v_div_fixup_f32 v225, v69, v68, v225
	v_mul_f32_e32 v38, v225, v38
	s_nop 1
	v_mov_b32_dpp v68, v6 quad_perm:[1,0,3,2] row_mask:0xf bank_mask:0xf
	v_mov_b32_dpp v69, v22 quad_perm:[1,0,3,2] row_mask:0xf bank_mask:0xf
	v_mov_b32_dpp v70, v38 quad_perm:[1,0,3,2] row_mask:0xf bank_mask:0xf
	s_nop 0
	v_cvt_pk_bf16_f32 v6, v6, v68
	v_cvt_pk_bf16_f32 v22, v22, v69
	v_cvt_pk_bf16_f32 v38, v38, v70
	s_mov_b64 exec, s[98:99]
	global_store_dword v202, v6, s[38:39]
	global_store_dword v202, v22, s[38:39] offset:256
	global_store_dword v202, v38, s[38:39] offset:512
	s_mov_b64 exec, -1
	v_add_u32_e32 v202, 0x1000, v202
	s_waitcnt lgkmcnt(0)
	v_add_f32_e32 v68, v64, v65
	v_add_f32_e32 v69, v66, v67
	ds_read_b128 v[64:67], v203 offset:256
	v_add_f32_e32 v68, v68, v69
	v_fmamk_f32 v68, v68, 0x3b2aaaab, v76
	v_mul_f32_e32 v69, 0x4b800000, v68
	v_cmp_gt_f32_e32 vcc, s56, v68
	s_nop 1
	v_cndmask_b32_e32 v68, v68, v69, vcc
	v_rsq_f32_e32 v68, v68
	s_nop 0
	v_mul_f32_e32 v69, 0x45800000, v68
	v_cndmask_b32_e32 v63, v68, v69, vcc
	s_waitcnt vmcnt(47)
	v_lshlrev_b32_e32 v226, 16, v226
	v_add_f32_e32 v226, v195, v226
	v_mul_f32_e32 v68, 0xbfb8aa3b, v226
	v_exp_f32_e32 v68, v68
	v_mul_f32_e32 v7, v7, v63
	v_add_f32_e32 v68, 1.0, v68
	v_div_scale_f32 v69, s[0:1], v68, v68, v226
	v_div_scale_f32 v71, vcc, v226, v68, v226
	v_rcp_f32_e32 v70, v69
	v_mul_f32_e32 v7, v198, v7
	v_fma_f32 v50, -v69, v70, 1.0
	v_fmac_f32_e32 v70, v50, v70
	v_mul_f32_e32 v50, v71, v70
	v_fma_f32 v51, -v69, v50, v71
	v_fmac_f32_e32 v50, v51, v70
	v_fma_f32 v69, -v69, v50, v71
	v_div_fmas_f32 v69, v69, v70, v50
	v_div_fixup_f32 v226, v69, v68, v226
	v_mul_f32_e32 v7, v226, v7
	s_waitcnt vmcnt(46)
	v_lshlrev_b32_e32 v227, 16, v227
	v_add_f32_e32 v227, v196, v227
	v_mul_f32_e32 v68, 0xbfb8aa3b, v227
	v_exp_f32_e32 v68, v68
	v_mul_f32_e32 v23, v23, v63
	v_add_f32_e32 v68, 1.0, v68
	v_div_scale_f32 v69, s[0:1], v68, v68, v227
	v_div_scale_f32 v71, vcc, v227, v68, v227
	v_rcp_f32_e32 v70, v69
	v_mul_f32_e32 v23, v199, v23
	v_fma_f32 v50, -v69, v70, 1.0
	v_fmac_f32_e32 v70, v50, v70
	v_mul_f32_e32 v50, v71, v70
	v_fma_f32 v51, -v69, v50, v71
	v_fmac_f32_e32 v50, v51, v70
	v_fma_f32 v69, -v69, v50, v71
	v_div_fmas_f32 v69, v69, v70, v50
	v_div_fixup_f32 v227, v69, v68, v227
	v_mul_f32_e32 v23, v227, v23
	s_waitcnt vmcnt(45)
	v_lshlrev_b32_e32 v228, 16, v228
	v_add_f32_e32 v228, v197, v228
	v_mul_f32_e32 v68, 0xbfb8aa3b, v228
	v_exp_f32_e32 v68, v68
	v_mul_f32_e32 v39, v39, v63
	v_add_f32_e32 v68, 1.0, v68
	v_div_scale_f32 v69, s[0:1], v68, v68, v228
	v_div_scale_f32 v71, vcc, v228, v68, v228
	v_rcp_f32_e32 v70, v69
	v_mul_f32_e32 v39, v200, v39
	v_fma_f32 v50, -v69, v70, 1.0
	v_fmac_f32_e32 v70, v50, v70
	v_mul_f32_e32 v50, v71, v70
	v_fma_f32 v51, -v69, v50, v71
	v_fmac_f32_e32 v50, v51, v70
	v_fma_f32 v69, -v69, v50, v71
	v_div_fmas_f32 v69, v69, v70, v50
	v_div_fixup_f32 v228, v69, v68, v228
	v_mul_f32_e32 v39, v228, v39
	s_nop 1
	v_mov_b32_dpp v68, v7 quad_perm:[1,0,3,2] row_mask:0xf bank_mask:0xf
	v_mov_b32_dpp v69, v23 quad_perm:[1,0,3,2] row_mask:0xf bank_mask:0xf
	v_mov_b32_dpp v70, v39 quad_perm:[1,0,3,2] row_mask:0xf bank_mask:0xf
	s_nop 0
	v_cvt_pk_bf16_f32 v7, v7, v68
	v_cvt_pk_bf16_f32 v23, v23, v69
	v_cvt_pk_bf16_f32 v39, v39, v70
	s_mov_b64 exec, s[98:99]
	global_store_dword v202, v7, s[38:39]
	global_store_dword v202, v23, s[38:39] offset:256
	global_store_dword v202, v39, s[38:39] offset:512
	s_mov_b64 exec, -1
	v_add_u32_e32 v202, 0x5000, v202
	s_waitcnt lgkmcnt(0)
	v_add_f32_e32 v68, v64, v65
	v_add_f32_e32 v69, v66, v67
	ds_read_b128 v[64:67], v203 offset:272
	v_add_f32_e32 v68, v68, v69
	v_fmamk_f32 v68, v68, 0x3b2aaaab, v76
	v_mul_f32_e32 v69, 0x4b800000, v68
	v_cmp_gt_f32_e32 vcc, s56, v68
	s_nop 1
	v_cndmask_b32_e32 v68, v68, v69, vcc
	v_rsq_f32_e32 v68, v68
	s_nop 0
	v_mul_f32_e32 v69, 0x45800000, v68
	v_cndmask_b32_e32 v63, v68, v69, vcc
	s_waitcnt vmcnt(47)
	v_lshlrev_b32_e32 v229, 16, v229
	v_add_f32_e32 v229, v195, v229
	v_mul_f32_e32 v68, 0xbfb8aa3b, v229
	v_exp_f32_e32 v68, v68
	v_mul_f32_e32 v8, v8, v63
	v_add_f32_e32 v68, 1.0, v68
	v_div_scale_f32 v69, s[0:1], v68, v68, v229
	v_div_scale_f32 v71, vcc, v229, v68, v229
	v_rcp_f32_e32 v70, v69
	v_mul_f32_e32 v8, v198, v8
	v_fma_f32 v50, -v69, v70, 1.0
	v_fmac_f32_e32 v70, v50, v70
	v_mul_f32_e32 v50, v71, v70
	v_fma_f32 v51, -v69, v50, v71
	v_fmac_f32_e32 v50, v51, v70
	v_fma_f32 v69, -v69, v50, v71
	v_div_fmas_f32 v69, v69, v70, v50
	v_div_fixup_f32 v229, v69, v68, v229
	v_mul_f32_e32 v8, v229, v8
	s_waitcnt vmcnt(46)
	v_lshlrev_b32_e32 v230, 16, v230
	v_add_f32_e32 v230, v196, v230
	v_mul_f32_e32 v68, 0xbfb8aa3b, v230
	v_exp_f32_e32 v68, v68
	v_mul_f32_e32 v24, v24, v63
	v_add_f32_e32 v68, 1.0, v68
	v_div_scale_f32 v69, s[0:1], v68, v68, v230
	v_div_scale_f32 v71, vcc, v230, v68, v230
	v_rcp_f32_e32 v70, v69
	v_mul_f32_e32 v24, v199, v24
	v_fma_f32 v50, -v69, v70, 1.0
	v_fmac_f32_e32 v70, v50, v70
	v_mul_f32_e32 v50, v71, v70
	v_fma_f32 v51, -v69, v50, v71
	v_fmac_f32_e32 v50, v51, v70
	v_fma_f32 v69, -v69, v50, v71
	v_div_fmas_f32 v69, v69, v70, v50
	v_div_fixup_f32 v230, v69, v68, v230
	v_mul_f32_e32 v24, v230, v24
	s_waitcnt vmcnt(45)
	v_lshlrev_b32_e32 v231, 16, v231
	v_add_f32_e32 v231, v197, v231
	v_mul_f32_e32 v68, 0xbfb8aa3b, v231
	v_exp_f32_e32 v68, v68
	v_mul_f32_e32 v40, v40, v63
	v_add_f32_e32 v68, 1.0, v68
	v_div_scale_f32 v69, s[0:1], v68, v68, v231
	v_div_scale_f32 v71, vcc, v231, v68, v231
	v_rcp_f32_e32 v70, v69
	v_mul_f32_e32 v40, v200, v40
	v_fma_f32 v50, -v69, v70, 1.0
	v_fmac_f32_e32 v70, v50, v70
	v_mul_f32_e32 v50, v71, v70
	v_fma_f32 v51, -v69, v50, v71
	v_fmac_f32_e32 v50, v51, v70
	v_fma_f32 v69, -v69, v50, v71
	v_div_fmas_f32 v69, v69, v70, v50
	v_div_fixup_f32 v231, v69, v68, v231
	v_mul_f32_e32 v40, v231, v40
	s_nop 1
	v_mov_b32_dpp v68, v8 quad_perm:[1,0,3,2] row_mask:0xf bank_mask:0xf
	v_mov_b32_dpp v69, v24 quad_perm:[1,0,3,2] row_mask:0xf bank_mask:0xf
	v_mov_b32_dpp v70, v40 quad_perm:[1,0,3,2] row_mask:0xf bank_mask:0xf
	s_nop 0
	v_cvt_pk_bf16_f32 v8, v8, v68
	v_cvt_pk_bf16_f32 v24, v24, v69
	v_cvt_pk_bf16_f32 v40, v40, v70
	s_mov_b64 exec, s[98:99]
	global_store_dword v202, v8, s[38:39]
	global_store_dword v202, v24, s[38:39] offset:256
	global_store_dword v202, v40, s[38:39] offset:512
	s_mov_b64 exec, -1
	v_add_u32_e32 v202, 0x1000, v202
	s_waitcnt lgkmcnt(0)
	v_add_f32_e32 v68, v64, v65
	v_add_f32_e32 v69, v66, v67
	ds_read_b128 v[64:67], v203 offset:288
	v_add_f32_e32 v68, v68, v69
	v_fmamk_f32 v68, v68, 0x3b2aaaab, v76
	v_mul_f32_e32 v69, 0x4b800000, v68
	v_cmp_gt_f32_e32 vcc, s56, v68
	s_nop 1
	v_cndmask_b32_e32 v68, v68, v69, vcc
	v_rsq_f32_e32 v68, v68
	s_nop 0
	v_mul_f32_e32 v69, 0x45800000, v68
	v_cndmask_b32_e32 v63, v68, v69, vcc
	s_waitcnt vmcnt(47)
	v_lshlrev_b32_e32 v232, 16, v232
	v_add_f32_e32 v232, v195, v232
	v_mul_f32_e32 v68, 0xbfb8aa3b, v232
	v_exp_f32_e32 v68, v68
	v_mul_f32_e32 v9, v9, v63
	v_add_f32_e32 v68, 1.0, v68
	v_div_scale_f32 v69, s[0:1], v68, v68, v232
	v_div_scale_f32 v71, vcc, v232, v68, v232
	v_rcp_f32_e32 v70, v69
	v_mul_f32_e32 v9, v198, v9
	v_fma_f32 v50, -v69, v70, 1.0
	v_fmac_f32_e32 v70, v50, v70
	v_mul_f32_e32 v50, v71, v70
	v_fma_f32 v51, -v69, v50, v71
	v_fmac_f32_e32 v50, v51, v70
	v_fma_f32 v69, -v69, v50, v71
	v_div_fmas_f32 v69, v69, v70, v50
	v_div_fixup_f32 v232, v69, v68, v232
	v_mul_f32_e32 v9, v232, v9
	s_waitcnt vmcnt(46)
	v_lshlrev_b32_e32 v233, 16, v233
	v_add_f32_e32 v233, v196, v233
	v_mul_f32_e32 v68, 0xbfb8aa3b, v233
	v_exp_f32_e32 v68, v68
	v_mul_f32_e32 v25, v25, v63
	v_add_f32_e32 v68, 1.0, v68
	v_div_scale_f32 v69, s[0:1], v68, v68, v233
	v_div_scale_f32 v71, vcc, v233, v68, v233
	v_rcp_f32_e32 v70, v69
	v_mul_f32_e32 v25, v199, v25
	v_fma_f32 v50, -v69, v70, 1.0
	v_fmac_f32_e32 v70, v50, v70
	v_mul_f32_e32 v50, v71, v70
	v_fma_f32 v51, -v69, v50, v71
	v_fmac_f32_e32 v50, v51, v70
	v_fma_f32 v69, -v69, v50, v71
	v_div_fmas_f32 v69, v69, v70, v50
	v_div_fixup_f32 v233, v69, v68, v233
	v_mul_f32_e32 v25, v233, v25
	s_waitcnt vmcnt(45)
	v_lshlrev_b32_e32 v234, 16, v234
	v_add_f32_e32 v234, v197, v234
	v_mul_f32_e32 v68, 0xbfb8aa3b, v234
	v_exp_f32_e32 v68, v68
	v_mul_f32_e32 v41, v41, v63
	v_add_f32_e32 v68, 1.0, v68
	v_div_scale_f32 v69, s[0:1], v68, v68, v234
	v_div_scale_f32 v71, vcc, v234, v68, v234
	v_rcp_f32_e32 v70, v69
	v_mul_f32_e32 v41, v200, v41
	v_fma_f32 v50, -v69, v70, 1.0
	v_fmac_f32_e32 v70, v50, v70
	v_mul_f32_e32 v50, v71, v70
	v_fma_f32 v51, -v69, v50, v71
	v_fmac_f32_e32 v50, v51, v70
	v_fma_f32 v69, -v69, v50, v71
	v_div_fmas_f32 v69, v69, v70, v50
	v_div_fixup_f32 v234, v69, v68, v234
	v_mul_f32_e32 v41, v234, v41
	s_nop 1
	v_mov_b32_dpp v68, v9 quad_perm:[1,0,3,2] row_mask:0xf bank_mask:0xf
	v_mov_b32_dpp v69, v25 quad_perm:[1,0,3,2] row_mask:0xf bank_mask:0xf
	v_mov_b32_dpp v70, v41 quad_perm:[1,0,3,2] row_mask:0xf bank_mask:0xf
	s_nop 0
	v_cvt_pk_bf16_f32 v9, v9, v68
	v_cvt_pk_bf16_f32 v25, v25, v69
	v_cvt_pk_bf16_f32 v41, v41, v70
	s_mov_b64 exec, s[98:99]
	global_store_dword v202, v9, s[38:39]
	global_store_dword v202, v25, s[38:39] offset:256
	global_store_dword v202, v41, s[38:39] offset:512
	s_mov_b64 exec, -1
	v_add_u32_e32 v202, 0x1000, v202
	s_waitcnt lgkmcnt(0)
	v_add_f32_e32 v68, v64, v65
	v_add_f32_e32 v69, v66, v67
	ds_read_b128 v[64:67], v203 offset:304
	v_add_f32_e32 v68, v68, v69
	v_fmamk_f32 v68, v68, 0x3b2aaaab, v76
	v_mul_f32_e32 v69, 0x4b800000, v68
	v_cmp_gt_f32_e32 vcc, s56, v68
	s_nop 1
	v_cndmask_b32_e32 v68, v68, v69, vcc
	v_rsq_f32_e32 v68, v68
	s_nop 0
	v_mul_f32_e32 v69, 0x45800000, v68
	v_cndmask_b32_e32 v63, v68, v69, vcc
	s_waitcnt vmcnt(47)
	v_lshlrev_b32_e32 v235, 16, v235
	v_add_f32_e32 v235, v195, v235
	v_mul_f32_e32 v68, 0xbfb8aa3b, v235
	v_exp_f32_e32 v68, v68
	v_mul_f32_e32 v10, v10, v63
	v_add_f32_e32 v68, 1.0, v68
	v_div_scale_f32 v69, s[0:1], v68, v68, v235
	v_div_scale_f32 v71, vcc, v235, v68, v235
	v_rcp_f32_e32 v70, v69
	v_mul_f32_e32 v10, v198, v10
	v_fma_f32 v50, -v69, v70, 1.0
	v_fmac_f32_e32 v70, v50, v70
	v_mul_f32_e32 v50, v71, v70
	v_fma_f32 v51, -v69, v50, v71
	v_fmac_f32_e32 v50, v51, v70
	v_fma_f32 v69, -v69, v50, v71
	v_div_fmas_f32 v69, v69, v70, v50
	v_div_fixup_f32 v235, v69, v68, v235
	v_mul_f32_e32 v10, v235, v10
	s_waitcnt vmcnt(46)
	v_lshlrev_b32_e32 v236, 16, v236
	v_add_f32_e32 v236, v196, v236
	v_mul_f32_e32 v68, 0xbfb8aa3b, v236
	v_exp_f32_e32 v68, v68
	v_mul_f32_e32 v26, v26, v63
	v_add_f32_e32 v68, 1.0, v68
	v_div_scale_f32 v69, s[0:1], v68, v68, v236
	v_div_scale_f32 v71, vcc, v236, v68, v236
	v_rcp_f32_e32 v70, v69
	v_mul_f32_e32 v26, v199, v26
	v_fma_f32 v50, -v69, v70, 1.0
	v_fmac_f32_e32 v70, v50, v70
	v_mul_f32_e32 v50, v71, v70
	v_fma_f32 v51, -v69, v50, v71
	v_fmac_f32_e32 v50, v51, v70
	v_fma_f32 v69, -v69, v50, v71
	v_div_fmas_f32 v69, v69, v70, v50
	v_div_fixup_f32 v236, v69, v68, v236
	v_mul_f32_e32 v26, v236, v26
	s_waitcnt vmcnt(45)
	v_lshlrev_b32_e32 v237, 16, v237
	v_add_f32_e32 v237, v197, v237
	v_mul_f32_e32 v68, 0xbfb8aa3b, v237
	v_exp_f32_e32 v68, v68
	v_mul_f32_e32 v42, v42, v63
	v_add_f32_e32 v68, 1.0, v68
	v_div_scale_f32 v69, s[0:1], v68, v68, v237
	v_div_scale_f32 v71, vcc, v237, v68, v237
	v_rcp_f32_e32 v70, v69
	v_mul_f32_e32 v42, v200, v42
	v_fma_f32 v50, -v69, v70, 1.0
	v_fmac_f32_e32 v70, v50, v70
	v_mul_f32_e32 v50, v71, v70
	v_fma_f32 v51, -v69, v50, v71
	v_fmac_f32_e32 v50, v51, v70
	v_fma_f32 v69, -v69, v50, v71
	v_div_fmas_f32 v69, v69, v70, v50
	v_div_fixup_f32 v237, v69, v68, v237
	v_mul_f32_e32 v42, v237, v42
	s_nop 1
	v_mov_b32_dpp v68, v10 quad_perm:[1,0,3,2] row_mask:0xf bank_mask:0xf
	v_mov_b32_dpp v69, v26 quad_perm:[1,0,3,2] row_mask:0xf bank_mask:0xf
	v_mov_b32_dpp v70, v42 quad_perm:[1,0,3,2] row_mask:0xf bank_mask:0xf
	s_nop 0
	v_cvt_pk_bf16_f32 v10, v10, v68
	v_cvt_pk_bf16_f32 v26, v26, v69
	v_cvt_pk_bf16_f32 v42, v42, v70
	s_mov_b64 exec, s[98:99]
	global_store_dword v202, v10, s[38:39]
	global_store_dword v202, v26, s[38:39] offset:256
	global_store_dword v202, v42, s[38:39] offset:512
	s_mov_b64 exec, -1
	v_add_u32_e32 v202, 0x1000, v202
	s_waitcnt lgkmcnt(0)
	v_add_f32_e32 v68, v64, v65
	v_add_f32_e32 v69, v66, v67
	ds_read_b128 v[64:67], v203 offset:384
	v_add_f32_e32 v68, v68, v69
	v_fmamk_f32 v68, v68, 0x3b2aaaab, v76
	v_mul_f32_e32 v69, 0x4b800000, v68
	v_cmp_gt_f32_e32 vcc, s56, v68
	s_nop 1
	v_cndmask_b32_e32 v68, v68, v69, vcc
	v_rsq_f32_e32 v68, v68
	s_nop 0
	v_mul_f32_e32 v69, 0x45800000, v68
	v_cndmask_b32_e32 v63, v68, v69, vcc
	s_waitcnt vmcnt(47)
	v_lshlrev_b32_e32 v238, 16, v238
	v_add_f32_e32 v238, v195, v238
	v_mul_f32_e32 v68, 0xbfb8aa3b, v238
	v_exp_f32_e32 v68, v68
	v_mul_f32_e32 v11, v11, v63
	v_add_f32_e32 v68, 1.0, v68
	v_div_scale_f32 v69, s[0:1], v68, v68, v238
	v_div_scale_f32 v71, vcc, v238, v68, v238
	v_rcp_f32_e32 v70, v69
	v_mul_f32_e32 v11, v198, v11
	v_fma_f32 v50, -v69, v70, 1.0
	v_fmac_f32_e32 v70, v50, v70
	v_mul_f32_e32 v50, v71, v70
	v_fma_f32 v51, -v69, v50, v71
	v_fmac_f32_e32 v50, v51, v70
	v_fma_f32 v69, -v69, v50, v71
	v_div_fmas_f32 v69, v69, v70, v50
	v_div_fixup_f32 v238, v69, v68, v238
	v_mul_f32_e32 v11, v238, v11
	s_waitcnt vmcnt(46)
	v_lshlrev_b32_e32 v239, 16, v239
	v_add_f32_e32 v239, v196, v239
	v_mul_f32_e32 v68, 0xbfb8aa3b, v239
	v_exp_f32_e32 v68, v68
	v_mul_f32_e32 v27, v27, v63
	v_add_f32_e32 v68, 1.0, v68
	v_div_scale_f32 v69, s[0:1], v68, v68, v239
	v_div_scale_f32 v71, vcc, v239, v68, v239
	v_rcp_f32_e32 v70, v69
	v_mul_f32_e32 v27, v199, v27
	v_fma_f32 v50, -v69, v70, 1.0
	v_fmac_f32_e32 v70, v50, v70
	v_mul_f32_e32 v50, v71, v70
	v_fma_f32 v51, -v69, v50, v71
	v_fmac_f32_e32 v50, v51, v70
	v_fma_f32 v69, -v69, v50, v71
	v_div_fmas_f32 v69, v69, v70, v50
	v_div_fixup_f32 v239, v69, v68, v239
	v_mul_f32_e32 v27, v239, v27
	s_waitcnt vmcnt(45)
	v_lshlrev_b32_e32 v240, 16, v240
	v_add_f32_e32 v240, v197, v240
	v_mul_f32_e32 v68, 0xbfb8aa3b, v240
	v_exp_f32_e32 v68, v68
	v_mul_f32_e32 v43, v43, v63
	v_add_f32_e32 v68, 1.0, v68
	v_div_scale_f32 v69, s[0:1], v68, v68, v240
	v_div_scale_f32 v71, vcc, v240, v68, v240
	v_rcp_f32_e32 v70, v69
	v_mul_f32_e32 v43, v200, v43
	v_fma_f32 v50, -v69, v70, 1.0
	v_fmac_f32_e32 v70, v50, v70
	v_mul_f32_e32 v50, v71, v70
	v_fma_f32 v51, -v69, v50, v71
	v_fmac_f32_e32 v50, v51, v70
	v_fma_f32 v69, -v69, v50, v71
	v_div_fmas_f32 v69, v69, v70, v50
	v_div_fixup_f32 v240, v69, v68, v240
	v_mul_f32_e32 v43, v240, v43
	s_nop 1
	v_mov_b32_dpp v68, v11 quad_perm:[1,0,3,2] row_mask:0xf bank_mask:0xf
	v_mov_b32_dpp v69, v27 quad_perm:[1,0,3,2] row_mask:0xf bank_mask:0xf
	v_mov_b32_dpp v70, v43 quad_perm:[1,0,3,2] row_mask:0xf bank_mask:0xf
	s_nop 0
	v_cvt_pk_bf16_f32 v11, v11, v68
	v_cvt_pk_bf16_f32 v27, v27, v69
	v_cvt_pk_bf16_f32 v43, v43, v70
	s_mov_b64 exec, s[98:99]
	global_store_dword v202, v11, s[38:39]
	global_store_dword v202, v27, s[38:39] offset:256
	global_store_dword v202, v43, s[38:39] offset:512
	s_mov_b64 exec, -1
	v_add_u32_e32 v202, 0x5000, v202
	s_waitcnt lgkmcnt(0)
	v_add_f32_e32 v68, v64, v65
	v_add_f32_e32 v69, v66, v67
	ds_read_b128 v[64:67], v203 offset:400
	v_add_f32_e32 v68, v68, v69
	v_fmamk_f32 v68, v68, 0x3b2aaaab, v76
	v_mul_f32_e32 v69, 0x4b800000, v68
	v_cmp_gt_f32_e32 vcc, s56, v68
	s_nop 1
	v_cndmask_b32_e32 v68, v68, v69, vcc
	v_rsq_f32_e32 v68, v68
	s_nop 0
	v_mul_f32_e32 v69, 0x45800000, v68
	v_cndmask_b32_e32 v63, v68, v69, vcc
	s_waitcnt vmcnt(47)
	v_lshlrev_b32_e32 v241, 16, v241
	v_add_f32_e32 v241, v195, v241
	v_mul_f32_e32 v68, 0xbfb8aa3b, v241
	v_exp_f32_e32 v68, v68
	v_mul_f32_e32 v12, v12, v63
	v_add_f32_e32 v68, 1.0, v68
	v_div_scale_f32 v69, s[0:1], v68, v68, v241
	v_div_scale_f32 v71, vcc, v241, v68, v241
	v_rcp_f32_e32 v70, v69
	v_mul_f32_e32 v12, v198, v12
	v_fma_f32 v50, -v69, v70, 1.0
	v_fmac_f32_e32 v70, v50, v70
	v_mul_f32_e32 v50, v71, v70
	v_fma_f32 v51, -v69, v50, v71
	v_fmac_f32_e32 v50, v51, v70
	v_fma_f32 v69, -v69, v50, v71
	v_div_fmas_f32 v69, v69, v70, v50
	v_div_fixup_f32 v241, v69, v68, v241
	v_mul_f32_e32 v12, v241, v12
	s_waitcnt vmcnt(46)
	v_lshlrev_b32_e32 v242, 16, v242
	v_add_f32_e32 v242, v196, v242
	v_mul_f32_e32 v68, 0xbfb8aa3b, v242
	v_exp_f32_e32 v68, v68
	v_mul_f32_e32 v28, v28, v63
	v_add_f32_e32 v68, 1.0, v68
	v_div_scale_f32 v69, s[0:1], v68, v68, v242
	v_div_scale_f32 v71, vcc, v242, v68, v242
	v_rcp_f32_e32 v70, v69
	v_mul_f32_e32 v28, v199, v28
	v_fma_f32 v50, -v69, v70, 1.0
	v_fmac_f32_e32 v70, v50, v70
	v_mul_f32_e32 v50, v71, v70
	v_fma_f32 v51, -v69, v50, v71
	v_fmac_f32_e32 v50, v51, v70
	v_fma_f32 v69, -v69, v50, v71
	v_div_fmas_f32 v69, v69, v70, v50
	v_div_fixup_f32 v242, v69, v68, v242
	v_mul_f32_e32 v28, v242, v28
	s_waitcnt vmcnt(45)
	v_lshlrev_b32_e32 v243, 16, v243
	v_add_f32_e32 v243, v197, v243
	v_mul_f32_e32 v68, 0xbfb8aa3b, v243
	v_exp_f32_e32 v68, v68
	v_mul_f32_e32 v44, v44, v63
	v_add_f32_e32 v68, 1.0, v68
	v_div_scale_f32 v69, s[0:1], v68, v68, v243
	v_div_scale_f32 v71, vcc, v243, v68, v243
	v_rcp_f32_e32 v70, v69
	v_mul_f32_e32 v44, v200, v44
	v_fma_f32 v50, -v69, v70, 1.0
	v_fmac_f32_e32 v70, v50, v70
	v_mul_f32_e32 v50, v71, v70
	v_fma_f32 v51, -v69, v50, v71
	v_fmac_f32_e32 v50, v51, v70
	v_fma_f32 v69, -v69, v50, v71
	v_div_fmas_f32 v69, v69, v70, v50
	v_div_fixup_f32 v243, v69, v68, v243
	v_mul_f32_e32 v44, v243, v44
	s_nop 1
	v_mov_b32_dpp v68, v12 quad_perm:[1,0,3,2] row_mask:0xf bank_mask:0xf
	v_mov_b32_dpp v69, v28 quad_perm:[1,0,3,2] row_mask:0xf bank_mask:0xf
	v_mov_b32_dpp v70, v44 quad_perm:[1,0,3,2] row_mask:0xf bank_mask:0xf
	s_nop 0
	v_cvt_pk_bf16_f32 v12, v12, v68
	v_cvt_pk_bf16_f32 v28, v28, v69
	v_cvt_pk_bf16_f32 v44, v44, v70
	s_mov_b64 exec, s[98:99]
	global_store_dword v202, v12, s[38:39]
	global_store_dword v202, v28, s[38:39] offset:256
	global_store_dword v202, v44, s[38:39] offset:512
	s_mov_b64 exec, -1
	v_add_u32_e32 v202, 0x1000, v202
	s_waitcnt lgkmcnt(0)
	v_add_f32_e32 v68, v64, v65
	v_add_f32_e32 v69, v66, v67
	ds_read_b128 v[64:67], v203 offset:416
	v_add_f32_e32 v68, v68, v69
	v_fmamk_f32 v68, v68, 0x3b2aaaab, v76
	v_mul_f32_e32 v69, 0x4b800000, v68
	v_cmp_gt_f32_e32 vcc, s56, v68
	s_nop 1
	v_cndmask_b32_e32 v68, v68, v69, vcc
	v_rsq_f32_e32 v68, v68
	s_nop 0
	v_mul_f32_e32 v69, 0x45800000, v68
	v_cndmask_b32_e32 v63, v68, v69, vcc
	s_waitcnt vmcnt(47)
	v_lshlrev_b32_e32 v244, 16, v244
	v_add_f32_e32 v244, v195, v244
	v_mul_f32_e32 v68, 0xbfb8aa3b, v244
	v_exp_f32_e32 v68, v68
	v_mul_f32_e32 v13, v13, v63
	v_add_f32_e32 v68, 1.0, v68
	v_div_scale_f32 v69, s[0:1], v68, v68, v244
	v_div_scale_f32 v71, vcc, v244, v68, v244
	v_rcp_f32_e32 v70, v69
	v_mul_f32_e32 v13, v198, v13
	v_fma_f32 v50, -v69, v70, 1.0
	v_fmac_f32_e32 v70, v50, v70
	v_mul_f32_e32 v50, v71, v70
	v_fma_f32 v51, -v69, v50, v71
	v_fmac_f32_e32 v50, v51, v70
	v_fma_f32 v69, -v69, v50, v71
	v_div_fmas_f32 v69, v69, v70, v50
	v_div_fixup_f32 v244, v69, v68, v244
	v_mul_f32_e32 v13, v244, v13
	s_waitcnt vmcnt(46)
	v_lshlrev_b32_e32 v245, 16, v245
	v_add_f32_e32 v245, v196, v245
	v_mul_f32_e32 v68, 0xbfb8aa3b, v245
	v_exp_f32_e32 v68, v68
	v_mul_f32_e32 v29, v29, v63
	v_add_f32_e32 v68, 1.0, v68
	v_div_scale_f32 v69, s[0:1], v68, v68, v245
	v_div_scale_f32 v71, vcc, v245, v68, v245
	v_rcp_f32_e32 v70, v69
	v_mul_f32_e32 v29, v199, v29
	v_fma_f32 v50, -v69, v70, 1.0
	v_fmac_f32_e32 v70, v50, v70
	v_mul_f32_e32 v50, v71, v70
	v_fma_f32 v51, -v69, v50, v71
	v_fmac_f32_e32 v50, v51, v70
	v_fma_f32 v69, -v69, v50, v71
	v_div_fmas_f32 v69, v69, v70, v50
	v_div_fixup_f32 v245, v69, v68, v245
	v_mul_f32_e32 v29, v245, v29
	s_waitcnt vmcnt(45)
	v_lshlrev_b32_e32 v246, 16, v246
	v_add_f32_e32 v246, v197, v246
	v_mul_f32_e32 v68, 0xbfb8aa3b, v246
	v_exp_f32_e32 v68, v68
	v_mul_f32_e32 v45, v45, v63
	v_add_f32_e32 v68, 1.0, v68
	v_div_scale_f32 v69, s[0:1], v68, v68, v246
	v_div_scale_f32 v71, vcc, v246, v68, v246
	v_rcp_f32_e32 v70, v69
	v_mul_f32_e32 v45, v200, v45
	v_fma_f32 v50, -v69, v70, 1.0
	v_fmac_f32_e32 v70, v50, v70
	v_mul_f32_e32 v50, v71, v70
	v_fma_f32 v51, -v69, v50, v71
	v_fmac_f32_e32 v50, v51, v70
	v_fma_f32 v69, -v69, v50, v71
	v_div_fmas_f32 v69, v69, v70, v50
	v_div_fixup_f32 v246, v69, v68, v246
	v_mul_f32_e32 v45, v246, v45
	s_nop 1
	v_mov_b32_dpp v68, v13 quad_perm:[1,0,3,2] row_mask:0xf bank_mask:0xf
	v_mov_b32_dpp v69, v29 quad_perm:[1,0,3,2] row_mask:0xf bank_mask:0xf
	v_mov_b32_dpp v70, v45 quad_perm:[1,0,3,2] row_mask:0xf bank_mask:0xf
	s_nop 0
	v_cvt_pk_bf16_f32 v13, v13, v68
	v_cvt_pk_bf16_f32 v29, v29, v69
	v_cvt_pk_bf16_f32 v45, v45, v70
	s_mov_b64 exec, s[98:99]
	global_store_dword v202, v13, s[38:39]
	global_store_dword v202, v29, s[38:39] offset:256
	global_store_dword v202, v45, s[38:39] offset:512
	s_mov_b64 exec, -1
	v_add_u32_e32 v202, 0x1000, v202
	s_waitcnt lgkmcnt(0)
	v_add_f32_e32 v68, v64, v65
	v_add_f32_e32 v69, v66, v67
	ds_read_b128 v[64:67], v203 offset:432
	v_add_f32_e32 v68, v68, v69
	v_fmamk_f32 v68, v68, 0x3b2aaaab, v76
	v_mul_f32_e32 v69, 0x4b800000, v68
	v_cmp_gt_f32_e32 vcc, s56, v68
	s_nop 1
	v_cndmask_b32_e32 v68, v68, v69, vcc
	v_rsq_f32_e32 v68, v68
	s_nop 0
	v_mul_f32_e32 v69, 0x45800000, v68
	v_cndmask_b32_e32 v63, v68, v69, vcc
	s_waitcnt vmcnt(47)
	v_lshlrev_b32_e32 v247, 16, v247
	v_add_f32_e32 v247, v195, v247
	v_mul_f32_e32 v68, 0xbfb8aa3b, v247
	v_exp_f32_e32 v68, v68
	v_mul_f32_e32 v14, v14, v63
	v_add_f32_e32 v68, 1.0, v68
	v_div_scale_f32 v69, s[0:1], v68, v68, v247
	v_div_scale_f32 v71, vcc, v247, v68, v247
	v_rcp_f32_e32 v70, v69
	v_mul_f32_e32 v14, v198, v14
	v_fma_f32 v50, -v69, v70, 1.0
	v_fmac_f32_e32 v70, v50, v70
	v_mul_f32_e32 v50, v71, v70
	v_fma_f32 v51, -v69, v50, v71
	v_fmac_f32_e32 v50, v51, v70
	v_fma_f32 v69, -v69, v50, v71
	v_div_fmas_f32 v69, v69, v70, v50
	v_div_fixup_f32 v247, v69, v68, v247
	v_mul_f32_e32 v14, v247, v14
	s_waitcnt vmcnt(46)
	v_lshlrev_b32_e32 v248, 16, v248
	v_add_f32_e32 v248, v196, v248
	v_mul_f32_e32 v68, 0xbfb8aa3b, v248
	v_exp_f32_e32 v68, v68
	v_mul_f32_e32 v30, v30, v63
	v_add_f32_e32 v68, 1.0, v68
	v_div_scale_f32 v69, s[0:1], v68, v68, v248
	v_div_scale_f32 v71, vcc, v248, v68, v248
	v_rcp_f32_e32 v70, v69
	v_mul_f32_e32 v30, v199, v30
	v_fma_f32 v50, -v69, v70, 1.0
	v_fmac_f32_e32 v70, v50, v70
	v_mul_f32_e32 v50, v71, v70
	v_fma_f32 v51, -v69, v50, v71
	v_fmac_f32_e32 v50, v51, v70
	v_fma_f32 v69, -v69, v50, v71
	v_div_fmas_f32 v69, v69, v70, v50
	v_div_fixup_f32 v248, v69, v68, v248
	v_mul_f32_e32 v30, v248, v30
	s_waitcnt vmcnt(45)
	v_lshlrev_b32_e32 v249, 16, v249
	v_add_f32_e32 v249, v197, v249
	v_mul_f32_e32 v68, 0xbfb8aa3b, v249
	v_exp_f32_e32 v68, v68
	v_mul_f32_e32 v46, v46, v63
	v_add_f32_e32 v68, 1.0, v68
	v_div_scale_f32 v69, s[0:1], v68, v68, v249
	v_div_scale_f32 v71, vcc, v249, v68, v249
	v_rcp_f32_e32 v70, v69
	v_mul_f32_e32 v46, v200, v46
	v_fma_f32 v50, -v69, v70, 1.0
	v_fmac_f32_e32 v70, v50, v70
	v_mul_f32_e32 v50, v71, v70
	v_fma_f32 v51, -v69, v50, v71
	v_fmac_f32_e32 v50, v51, v70
	v_fma_f32 v69, -v69, v50, v71
	v_div_fmas_f32 v69, v69, v70, v50
	v_div_fixup_f32 v249, v69, v68, v249
	v_mul_f32_e32 v46, v249, v46
	s_nop 1
	v_mov_b32_dpp v68, v14 quad_perm:[1,0,3,2] row_mask:0xf bank_mask:0xf
	v_mov_b32_dpp v69, v30 quad_perm:[1,0,3,2] row_mask:0xf bank_mask:0xf
	v_mov_b32_dpp v70, v46 quad_perm:[1,0,3,2] row_mask:0xf bank_mask:0xf
	s_nop 0
	v_cvt_pk_bf16_f32 v14, v14, v68
	v_cvt_pk_bf16_f32 v30, v30, v69
	v_cvt_pk_bf16_f32 v46, v46, v70
	s_mov_b64 exec, s[98:99]
	global_store_dword v202, v14, s[38:39]
	global_store_dword v202, v30, s[38:39] offset:256
	global_store_dword v202, v46, s[38:39] offset:512
	s_mov_b64 exec, -1
	v_add_u32_e32 v202, 0x1000, v202
	s_waitcnt lgkmcnt(0)
	v_add_f32_e32 v68, v64, v65
	v_add_f32_e32 v69, v66, v67
	v_add_f32_e32 v68, v68, v69
	v_fmamk_f32 v68, v68, 0x3b2aaaab, v76
	v_mul_f32_e32 v69, 0x4b800000, v68
	v_cmp_gt_f32_e32 vcc, s56, v68
	s_nop 1
	v_cndmask_b32_e32 v68, v68, v69, vcc
	v_rsq_f32_e32 v68, v68
	s_nop 0
	v_mul_f32_e32 v69, 0x45800000, v68
	v_cndmask_b32_e32 v63, v68, v69, vcc
	s_waitcnt vmcnt(47)
	v_lshlrev_b32_e32 v250, 16, v250
	v_add_f32_e32 v250, v195, v250
	v_mul_f32_e32 v68, 0xbfb8aa3b, v250
	v_exp_f32_e32 v68, v68
	v_mul_f32_e32 v15, v15, v63
	v_add_f32_e32 v68, 1.0, v68
	v_div_scale_f32 v69, s[0:1], v68, v68, v250
	v_div_scale_f32 v71, vcc, v250, v68, v250
	v_rcp_f32_e32 v70, v69
	v_mul_f32_e32 v15, v198, v15
	v_fma_f32 v50, -v69, v70, 1.0
	v_fmac_f32_e32 v70, v50, v70
	v_mul_f32_e32 v50, v71, v70
	v_fma_f32 v51, -v69, v50, v71
	v_fmac_f32_e32 v50, v51, v70
	v_fma_f32 v69, -v69, v50, v71
	v_div_fmas_f32 v69, v69, v70, v50
	v_div_fixup_f32 v250, v69, v68, v250
	v_mul_f32_e32 v15, v250, v15
	s_waitcnt vmcnt(46)
	v_lshlrev_b32_e32 v251, 16, v251
	v_add_f32_e32 v251, v196, v251
	v_mul_f32_e32 v68, 0xbfb8aa3b, v251
	v_exp_f32_e32 v68, v68
	v_mul_f32_e32 v31, v31, v63
	v_add_f32_e32 v68, 1.0, v68
	v_div_scale_f32 v69, s[0:1], v68, v68, v251
	v_div_scale_f32 v71, vcc, v251, v68, v251
	v_rcp_f32_e32 v70, v69
	v_mul_f32_e32 v31, v199, v31
	v_fma_f32 v50, -v69, v70, 1.0
	v_fmac_f32_e32 v70, v50, v70
	v_mul_f32_e32 v50, v71, v70
	v_fma_f32 v51, -v69, v50, v71
	v_fmac_f32_e32 v50, v51, v70
	v_fma_f32 v69, -v69, v50, v71
	v_div_fmas_f32 v69, v69, v70, v50
	v_div_fixup_f32 v251, v69, v68, v251
	v_mul_f32_e32 v31, v251, v31
	s_waitcnt vmcnt(45)
	v_lshlrev_b32_e32 v194, 16, v194
	v_add_f32_e32 v194, v197, v194
	v_mul_f32_e32 v68, 0xbfb8aa3b, v194
	v_exp_f32_e32 v68, v68
	v_mul_f32_e32 v47, v47, v63
	v_add_f32_e32 v68, 1.0, v68
	v_div_scale_f32 v69, s[0:1], v68, v68, v194
	v_div_scale_f32 v71, vcc, v194, v68, v194
	v_rcp_f32_e32 v70, v69
	v_mul_f32_e32 v47, v200, v47
	v_fma_f32 v50, -v69, v70, 1.0
	v_fmac_f32_e32 v70, v50, v70
	v_mul_f32_e32 v50, v71, v70
	v_fma_f32 v51, -v69, v50, v71
	v_fmac_f32_e32 v50, v51, v70
	v_fma_f32 v69, -v69, v50, v71
	v_div_fmas_f32 v69, v69, v70, v50
	v_div_fixup_f32 v194, v69, v68, v194
	v_mul_f32_e32 v47, v194, v47
	s_nop 1
	v_mov_b32_dpp v68, v15 quad_perm:[1,0,3,2] row_mask:0xf bank_mask:0xf
	v_mov_b32_dpp v69, v31 quad_perm:[1,0,3,2] row_mask:0xf bank_mask:0xf
	v_mov_b32_dpp v70, v47 quad_perm:[1,0,3,2] row_mask:0xf bank_mask:0xf
	s_nop 0
	v_cvt_pk_bf16_f32 v15, v15, v68
	v_cvt_pk_bf16_f32 v31, v31, v69
	v_cvt_pk_bf16_f32 v47, v47, v70
	s_mov_b64 exec, s[98:99]
	global_store_dword v202, v15, s[38:39]
	global_store_dword v202, v31, s[38:39] offset:256
	global_store_dword v202, v47, s[38:39] offset:512
	s_mov_b64 exec, -1
	s_branch .LBB0_4791
